# fused residual stages: sample-item workgroups touch the item's x/gob/ssq lines during E3 so its loads hit L2
# baseline (speedup 1.0000x reference)
.LBB0_852:
	s_or_b64 exec, exec, s[0:1]
	s_waitcnt lgkmcnt(0)
	s_barrier
	s_and_b32 s98, s2, 7
	s_lshl_b32 s98, s98, 3
	s_bfe_u32 s99, s2, 0x30003
	s_or_b32 s98, s98, s99
	s_lshr_b32 s99, s2, 6
	v_and_b32_e32 v172, 0xff, v136
	v_lshrrev_b32_e32 v173, 8, v136
	v_mul_u32_u24_e32 v173, 0x84000, v173
	v_lshl_add_u32 v172, v172, 2, v173
	s_lshl_b32 s24, s98, 10
	s_add_u32 s18, s44, s24
	s_addc_u32 s19, s45, 0
	global_load_dword v164, v172, s[18:19]
	s_add_u32 s18, s18, 0x10800
	s_addc_u32 s19, s19, 0
	global_load_dword v165, v172, s[18:19]
	s_add_u32 s18, s18, 0x10800
	s_addc_u32 s19, s19, 0
	global_load_dword v166, v172, s[18:19]
	s_add_u32 s18, s18, 0x10800
	s_addc_u32 s19, s19, 0
	global_load_dword v167, v172, s[18:19]
	s_add_u32 s18, s18, 0x10800
	s_addc_u32 s19, s19, 0
	global_load_dword v168, v172, s[18:19]
	s_add_u32 s18, s18, 0x10800
	s_addc_u32 s19, s19, 0
	global_load_dword v169, v172, s[18:19]
	s_add_u32 s18, s18, 0x10800
	s_addc_u32 s19, s19, 0
	global_load_dword v170, v172, s[18:19]
	s_add_u32 s18, s18, 0x10800
	s_addc_u32 s19, s19, 0
	global_load_dword v171, v172, s[18:19]
	v_lshrrev_b32_e32 v141, 8, v136
	v_and_b32_e32 v142, 15, v136
	v_lshl_add_u32 v141, v141, 6, v142
	v_bfe_u32 v144, v136, 6, 2
	v_bfe_u32 v145, v136, 4, 2
	v_lshlrev_b32_e32 v144, 5, v144
	v_lshl_add_u32 v144, v145, 3, v144
	s_lshl_b32 s24, s99, 8
	v_add_u32_e32 v144, s24, v144
	s_lshl_b32 s25, s98, 8
	v_add_u32_e32 v145, s25, v141
	v_lshl_add_u32 v146, v145, 10, v144
	v_lshlrev_b32_e32 v140, 1, v146
	v_lshlrev_b32_e32 v147, 2, v144
	v_readlane_b32 s18, v253, 3
	v_readlane_b32 s19, v253, 4
	v_readlane_b32 s20, v253, 53
	v_readlane_b32 s21, v253, 54
	s_nop 4
	s_add_u32 s18, s18, 0x1000
	s_addc_u32 s19, s19, 0
	global_load_dwordx4 v[148:151], v147, s[18:19]
	global_load_dwordx4 v[152:155], v147, s[18:19] offset:16
	global_load_dwordx4 v[156:159], v147, s[18:19] offset:512
	global_load_dwordx4 v[160:163], v147, s[18:19] offset:528
	s_add_u32 s22, s20, 0x0
	s_addc_u32 s23, s21, 0
	global_load_dwordx4 v[188:191], v140, s[22:23] nt
	global_load_dwordx4 v[192:195], v140, s[22:23] offset:256 nt
	s_add_u32 s22, s20, 0x8000
	s_addc_u32 s23, s21, 0
	global_load_dwordx4 v[196:199], v140, s[22:23] nt
	global_load_dwordx4 v[200:203], v140, s[22:23] offset:256 nt
	s_add_u32 s22, s20, 0x10000
	s_addc_u32 s23, s21, 0
	global_load_dwordx4 v[204:207], v140, s[22:23] nt
	global_load_dwordx4 v[208:211], v140, s[22:23] offset:256 nt
	s_add_u32 s22, s20, 0x18000
	s_addc_u32 s23, s21, 0
	global_load_dwordx4 v[212:215], v140, s[22:23] nt
	global_load_dwordx4 v[216:219], v140, s[22:23] offset:256 nt
	s_add_u32 s22, s20, 0x40000
	s_addc_u32 s23, s21, 0
	global_load_dwordx4 v[220:223], v140, s[22:23] nt
	global_load_dwordx4 v[224:227], v140, s[22:23] offset:256 nt
	s_add_u32 s22, s20, 0x48000
	s_addc_u32 s23, s21, 0
	global_load_dwordx4 v[228:231], v140, s[22:23] nt
	global_load_dwordx4 v[232:235], v140, s[22:23] offset:256 nt
	s_add_u32 s22, s20, 0x50000
	s_addc_u32 s23, s21, 0
	global_load_dwordx4 v[236:239], v140, s[22:23] nt
	global_load_dwordx4 v[240:243], v140, s[22:23] offset:256 nt
	s_add_u32 s22, s20, 0x58000
	s_addc_u32 s23, s21, 0
	global_load_dwordx4 v[244:247], v140, s[22:23] nt
	global_load_dwordx4 v[248:251], v140, s[22:23] offset:256 nt
	s_cmp_lt_u32 s2, 32
	s_cbranch_scc0 .Ltouch_0
	v_and_b32_e32 v185, 63, v136
	v_lshrrev_b32_e32 v186, 6, v136
	s_lshl_b32 s24, s2, 4
	s_add_i32 s24, s24, 0x4000
	v_lshl_add_u32 v186, v186, 1, s24
	v_lshlrev_b32_e32 v187, 11, v186
	v_lshl_add_u32 v187, v185, 6, v187
	global_load_dword v184, v187, s[20:21]
	global_load_dword v184, v187, s[58:59]
	v_and_b32_e32 v185, 15, v185
	v_mul_u32_u24_e32 v185, 0x10800, v185
	v_lshl_add_u32 v185, v186, 2, v185
	global_load_dword v184, v185, s[44:45]
.Ltouch_0:
	s_waitcnt vmcnt(20)
	v_add_f32_e32 v164, v164, v165
	v_add_f32_e32 v164, v164, v166
	v_add_f32_e32 v164, v164, v167
	v_add_f32_e32 v164, v164, v168
	v_add_f32_e32 v164, v164, v169
	v_add_f32_e32 v164, v164, v170
	v_add_f32_e32 v164, v164, v171
	v_lshlrev_b32_e32 v173, 2, v136
	ds_write_b32 v173, v164
	s_waitcnt lgkmcnt(0)
	s_barrier
	v_lshlrev_b32_e32 v142, 2, v141
	ds_read_b32 v128, v142 offset:0
	ds_read_b32 v174, v142 offset:1024
	ds_read_b32 v129, v142 offset:64
	ds_read_b32 v175, v142 offset:1088
	ds_read_b32 v130, v142 offset:128
	ds_read_b32 v176, v142 offset:1152
	ds_read_b32 v131, v142 offset:192
	ds_read_b32 v177, v142 offset:1216
	ds_read_b32 v132, v142 offset:512
	ds_read_b32 v178, v142 offset:1536
	ds_read_b32 v133, v142 offset:576
	ds_read_b32 v179, v142 offset:1600
	ds_read_b32 v134, v142 offset:640
	ds_read_b32 v180, v142 offset:1664
	ds_read_b32 v135, v142 offset:704
	ds_read_b32 v181, v142 offset:1728
	s_waitcnt lgkmcnt(0)
	s_mov_b32 s101, 0x3a800000
	v_mov_b32_e32 v143, 0x358637bd
	v_add_f32_e32 v128, v128, v174
	v_add_f32_e32 v129, v129, v175
	v_add_f32_e32 v130, v130, v176
	v_add_f32_e32 v131, v131, v177
	v_add_f32_e32 v132, v132, v178
	v_add_f32_e32 v133, v133, v179
	v_add_f32_e32 v134, v134, v180
	v_add_f32_e32 v135, v135, v181
	v_fma_f32 v128, v128, s101, v143
	v_fma_f32 v129, v129, s101, v143
	v_fma_f32 v130, v130, s101, v143
	v_fma_f32 v131, v131, s101, v143
	v_fma_f32 v132, v132, s101, v143
	v_fma_f32 v133, v133, s101, v143
	v_fma_f32 v134, v134, s101, v143
	v_fma_f32 v135, v135, s101, v143
	v_rsq_f32_e32 v128, v128
	v_rsq_f32_e32 v129, v129
	v_rsq_f32_e32 v130, v130
	v_rsq_f32_e32 v131, v131
	v_rsq_f32_e32 v132, v132
	v_rsq_f32_e32 v133, v133
	v_rsq_f32_e32 v134, v134
	v_rsq_f32_e32 v135, v135
	s_waitcnt vmcnt(0)
	s_add_u32 s22, s60, 0x0
	s_addc_u32 s23, s61, 0
	v_lshlrev_b32_e32 v164, 16, v188
	v_and_b32_e32 v165, 0xffff0000, v188
	v_lshlrev_b32_e32 v166, 16, v189
	v_and_b32_e32 v167, 0xffff0000, v189
	v_lshlrev_b32_e32 v168, 16, v190
	v_and_b32_e32 v169, 0xffff0000, v190
	v_lshlrev_b32_e32 v170, 16, v191
	v_and_b32_e32 v171, 0xffff0000, v191
	v_mul_f32_e32 v124, v124, v128
	v_mul_f32_e32 v125, v125, v128
	v_mul_f32_e32 v126, v126, v128
	v_mul_f32_e32 v127, v127, v128
	v_mul_f32_e32 v112, v112, v128
	v_mul_f32_e32 v113, v113, v128
	v_mul_f32_e32 v114, v114, v128
	v_mul_f32_e32 v115, v115, v128
	v_fmac_f32_e32 v164, v124, v148
	v_fmac_f32_e32 v165, v125, v149
	v_fmac_f32_e32 v166, v126, v150
	v_fmac_f32_e32 v167, v127, v151
	v_fmac_f32_e32 v168, v112, v152
	v_fmac_f32_e32 v169, v113, v153
	v_fmac_f32_e32 v170, v114, v154
	v_fmac_f32_e32 v171, v115, v155
	v_mul_f32_e32 v138, v164, v164
	v_fmac_f32_e32 v138, v165, v165
	v_fmac_f32_e32 v138, v166, v166
	v_fmac_f32_e32 v138, v167, v167
	v_fmac_f32_e32 v138, v168, v168
	v_fmac_f32_e32 v138, v169, v169
	v_fmac_f32_e32 v138, v170, v170
	v_fmac_f32_e32 v138, v171, v171
	v_cvt_pk_bf16_f32 v180, v164, v165
	v_cvt_pk_bf16_f32 v181, v166, v167
	v_cvt_pk_bf16_f32 v182, v168, v169
	v_cvt_pk_bf16_f32 v183, v170, v171
	global_store_dwordx4 v140, v[180:183], s[22:23]
	v_lshlrev_b32_e32 v172, 16, v192
	v_and_b32_e32 v173, 0xffff0000, v192
	v_lshlrev_b32_e32 v174, 16, v193
	v_and_b32_e32 v175, 0xffff0000, v193
	v_lshlrev_b32_e32 v176, 16, v194
	v_and_b32_e32 v177, 0xffff0000, v194
	v_lshlrev_b32_e32 v178, 16, v195
	v_and_b32_e32 v179, 0xffff0000, v195
	v_mul_f32_e32 v120, v120, v128
	v_mul_f32_e32 v121, v121, v128
	v_mul_f32_e32 v122, v122, v128
	v_mul_f32_e32 v123, v123, v128
	v_mul_f32_e32 v116, v116, v128
	v_mul_f32_e32 v117, v117, v128
	v_mul_f32_e32 v118, v118, v128
	v_mul_f32_e32 v119, v119, v128
	v_fmac_f32_e32 v172, v120, v156
	v_fmac_f32_e32 v173, v121, v157
	v_fmac_f32_e32 v174, v122, v158
	v_fmac_f32_e32 v175, v123, v159
	v_fmac_f32_e32 v176, v116, v160
	v_fmac_f32_e32 v177, v117, v161
	v_fmac_f32_e32 v178, v118, v162
	v_fmac_f32_e32 v179, v119, v163
	v_fmac_f32_e32 v138, v172, v172
	v_fmac_f32_e32 v138, v173, v173
	v_fmac_f32_e32 v138, v174, v174
	v_fmac_f32_e32 v138, v175, v175
	v_fmac_f32_e32 v138, v176, v176
	v_fmac_f32_e32 v138, v177, v177
	v_fmac_f32_e32 v138, v178, v178
	v_fmac_f32_e32 v138, v179, v179
	v_cvt_pk_bf16_f32 v184, v172, v173
	v_cvt_pk_bf16_f32 v185, v174, v175
	v_cvt_pk_bf16_f32 v186, v176, v177
	v_cvt_pk_bf16_f32 v187, v178, v179
	global_store_dwordx4 v140, v[184:187], s[22:23] offset:256
	s_add_u32 s22, s60, 0x8000
	s_addc_u32 s23, s61, 0
	v_lshlrev_b32_e32 v164, 16, v196
	v_and_b32_e32 v165, 0xffff0000, v196
	v_lshlrev_b32_e32 v166, 16, v197
	v_and_b32_e32 v167, 0xffff0000, v197
	v_lshlrev_b32_e32 v168, 16, v198
	v_and_b32_e32 v169, 0xffff0000, v198
	v_lshlrev_b32_e32 v170, 16, v199
	v_and_b32_e32 v171, 0xffff0000, v199
	v_mul_f32_e32 v108, v108, v129
	v_mul_f32_e32 v109, v109, v129
	v_mul_f32_e32 v110, v110, v129
	v_mul_f32_e32 v111, v111, v129
	v_mul_f32_e32 v96, v96, v129
	v_mul_f32_e32 v97, v97, v129
	v_mul_f32_e32 v98, v98, v129
	v_mul_f32_e32 v99, v99, v129
	v_fmac_f32_e32 v164, v108, v148
	v_fmac_f32_e32 v165, v109, v149
	v_fmac_f32_e32 v166, v110, v150
	v_fmac_f32_e32 v167, v111, v151
	v_fmac_f32_e32 v168, v96, v152
	v_fmac_f32_e32 v169, v97, v153
	v_fmac_f32_e32 v170, v98, v154
	v_fmac_f32_e32 v171, v99, v155
	v_mul_f32_e32 v139, v164, v164
	v_fmac_f32_e32 v139, v165, v165
	v_fmac_f32_e32 v139, v166, v166
	v_fmac_f32_e32 v139, v167, v167
	v_fmac_f32_e32 v139, v168, v168
	v_fmac_f32_e32 v139, v169, v169
	v_fmac_f32_e32 v139, v170, v170
	v_fmac_f32_e32 v139, v171, v171
	v_cvt_pk_bf16_f32 v180, v164, v165
	v_cvt_pk_bf16_f32 v181, v166, v167
	v_cvt_pk_bf16_f32 v182, v168, v169
	v_cvt_pk_bf16_f32 v183, v170, v171
	global_store_dwordx4 v140, v[180:183], s[22:23]
	v_lshlrev_b32_e32 v172, 16, v200
	v_and_b32_e32 v173, 0xffff0000, v200
	v_lshlrev_b32_e32 v174, 16, v201
	v_and_b32_e32 v175, 0xffff0000, v201
	v_lshlrev_b32_e32 v176, 16, v202
	v_and_b32_e32 v177, 0xffff0000, v202
	v_lshlrev_b32_e32 v178, 16, v203
	v_and_b32_e32 v179, 0xffff0000, v203
	v_mul_f32_e32 v100, v100, v129
	v_mul_f32_e32 v101, v101, v129
	v_mul_f32_e32 v102, v102, v129
	v_mul_f32_e32 v103, v103, v129
	v_mul_f32_e32 v104, v104, v129
	v_mul_f32_e32 v105, v105, v129
	v_mul_f32_e32 v106, v106, v129
	v_mul_f32_e32 v107, v107, v129
	v_fmac_f32_e32 v172, v100, v156
	v_fmac_f32_e32 v173, v101, v157
	v_fmac_f32_e32 v174, v102, v158
	v_fmac_f32_e32 v175, v103, v159
	v_fmac_f32_e32 v176, v104, v160
	v_fmac_f32_e32 v177, v105, v161
	v_fmac_f32_e32 v178, v106, v162
	v_fmac_f32_e32 v179, v107, v163
	v_fmac_f32_e32 v139, v172, v172
	v_fmac_f32_e32 v139, v173, v173
	v_fmac_f32_e32 v139, v174, v174
	v_fmac_f32_e32 v139, v175, v175
	v_fmac_f32_e32 v139, v176, v176
	v_fmac_f32_e32 v139, v177, v177
	v_fmac_f32_e32 v139, v178, v178
	v_fmac_f32_e32 v139, v179, v179
	v_cvt_pk_bf16_f32 v184, v172, v173
	v_cvt_pk_bf16_f32 v185, v174, v175
	v_cvt_pk_bf16_f32 v186, v176, v177
	v_cvt_pk_bf16_f32 v187, v178, v179
	global_store_dwordx4 v140, v[184:187], s[22:23] offset:256
	s_add_u32 s22, s60, 0x10000
	s_addc_u32 s23, s61, 0
	v_lshlrev_b32_e32 v164, 16, v204
	v_and_b32_e32 v165, 0xffff0000, v204
	v_lshlrev_b32_e32 v166, 16, v205
	v_and_b32_e32 v167, 0xffff0000, v205
	v_lshlrev_b32_e32 v168, 16, v206
	v_and_b32_e32 v169, 0xffff0000, v206
	v_lshlrev_b32_e32 v170, 16, v207
	v_and_b32_e32 v171, 0xffff0000, v207
	v_mul_f32_e32 v92, v92, v130
	v_mul_f32_e32 v93, v93, v130
	v_mul_f32_e32 v94, v94, v130
	v_mul_f32_e32 v95, v95, v130
	v_mul_f32_e32 v80, v80, v130
	v_mul_f32_e32 v81, v81, v130
	v_mul_f32_e32 v82, v82, v130
	v_mul_f32_e32 v83, v83, v130
	v_fmac_f32_e32 v164, v92, v148
	v_fmac_f32_e32 v165, v93, v149
	v_fmac_f32_e32 v166, v94, v150
	v_fmac_f32_e32 v167, v95, v151
	v_fmac_f32_e32 v168, v80, v152
	v_fmac_f32_e32 v169, v81, v153
	v_fmac_f32_e32 v170, v82, v154
	v_fmac_f32_e32 v171, v83, v155
	v_mul_f32_e32 v141, v164, v164
	v_fmac_f32_e32 v141, v165, v165
	v_fmac_f32_e32 v141, v166, v166
	v_fmac_f32_e32 v141, v167, v167
	v_fmac_f32_e32 v141, v168, v168
	v_fmac_f32_e32 v141, v169, v169
	v_fmac_f32_e32 v141, v170, v170
	v_fmac_f32_e32 v141, v171, v171
	v_cvt_pk_bf16_f32 v180, v164, v165
	v_cvt_pk_bf16_f32 v181, v166, v167
	v_cvt_pk_bf16_f32 v182, v168, v169
	v_cvt_pk_bf16_f32 v183, v170, v171
	global_store_dwordx4 v140, v[180:183], s[22:23]
	v_lshlrev_b32_e32 v172, 16, v208
	v_and_b32_e32 v173, 0xffff0000, v208
	v_lshlrev_b32_e32 v174, 16, v209
	v_and_b32_e32 v175, 0xffff0000, v209
	v_lshlrev_b32_e32 v176, 16, v210
	v_and_b32_e32 v177, 0xffff0000, v210
	v_lshlrev_b32_e32 v178, 16, v211
	v_and_b32_e32 v179, 0xffff0000, v211
	v_mul_f32_e32 v84, v84, v130
	v_mul_f32_e32 v85, v85, v130
	v_mul_f32_e32 v86, v86, v130
	v_mul_f32_e32 v87, v87, v130
	v_mul_f32_e32 v88, v88, v130
	v_mul_f32_e32 v89, v89, v130
	v_mul_f32_e32 v90, v90, v130
	v_mul_f32_e32 v91, v91, v130
	v_fmac_f32_e32 v172, v84, v156
	v_fmac_f32_e32 v173, v85, v157
	v_fmac_f32_e32 v174, v86, v158
	v_fmac_f32_e32 v175, v87, v159
	v_fmac_f32_e32 v176, v88, v160
	v_fmac_f32_e32 v177, v89, v161
	v_fmac_f32_e32 v178, v90, v162
	v_fmac_f32_e32 v179, v91, v163
	v_fmac_f32_e32 v141, v172, v172
	v_fmac_f32_e32 v141, v173, v173
	v_fmac_f32_e32 v141, v174, v174
	v_fmac_f32_e32 v141, v175, v175
	v_fmac_f32_e32 v141, v176, v176
	v_fmac_f32_e32 v141, v177, v177
	v_fmac_f32_e32 v141, v178, v178
	v_fmac_f32_e32 v141, v179, v179
	v_cvt_pk_bf16_f32 v184, v172, v173
	v_cvt_pk_bf16_f32 v185, v174, v175
	v_cvt_pk_bf16_f32 v186, v176, v177
	v_cvt_pk_bf16_f32 v187, v178, v179
	global_store_dwordx4 v140, v[184:187], s[22:23] offset:256
	s_add_u32 s22, s60, 0x18000
	s_addc_u32 s23, s61, 0
	v_lshlrev_b32_e32 v164, 16, v212
	v_and_b32_e32 v165, 0xffff0000, v212
	v_lshlrev_b32_e32 v166, 16, v213
	v_and_b32_e32 v167, 0xffff0000, v213
	v_lshlrev_b32_e32 v168, 16, v214
	v_and_b32_e32 v169, 0xffff0000, v214
	v_lshlrev_b32_e32 v170, 16, v215
	v_and_b32_e32 v171, 0xffff0000, v215
	v_mul_f32_e32 v76, v76, v131
	v_mul_f32_e32 v77, v77, v131
	v_mul_f32_e32 v78, v78, v131
	v_mul_f32_e32 v79, v79, v131
	v_mul_f32_e32 v64, v64, v131
	v_mul_f32_e32 v65, v65, v131
	v_mul_f32_e32 v66, v66, v131
	v_mul_f32_e32 v67, v67, v131
	v_fmac_f32_e32 v164, v76, v148
	v_fmac_f32_e32 v165, v77, v149
	v_fmac_f32_e32 v166, v78, v150
	v_fmac_f32_e32 v167, v79, v151
	v_fmac_f32_e32 v168, v64, v152
	v_fmac_f32_e32 v169, v65, v153
	v_fmac_f32_e32 v170, v66, v154
	v_fmac_f32_e32 v171, v67, v155
	v_mul_f32_e32 v142, v164, v164
	v_fmac_f32_e32 v142, v165, v165
	v_fmac_f32_e32 v142, v166, v166
	v_fmac_f32_e32 v142, v167, v167
	v_fmac_f32_e32 v142, v168, v168
	v_fmac_f32_e32 v142, v169, v169
	v_fmac_f32_e32 v142, v170, v170
	v_fmac_f32_e32 v142, v171, v171
	v_cvt_pk_bf16_f32 v180, v164, v165
	v_cvt_pk_bf16_f32 v181, v166, v167
	v_cvt_pk_bf16_f32 v182, v168, v169
	v_cvt_pk_bf16_f32 v183, v170, v171
	global_store_dwordx4 v140, v[180:183], s[22:23]
	v_lshlrev_b32_e32 v172, 16, v216
	v_and_b32_e32 v173, 0xffff0000, v216
	v_lshlrev_b32_e32 v174, 16, v217
	v_and_b32_e32 v175, 0xffff0000, v217
	v_lshlrev_b32_e32 v176, 16, v218
	v_and_b32_e32 v177, 0xffff0000, v218
	v_lshlrev_b32_e32 v178, 16, v219
	v_and_b32_e32 v179, 0xffff0000, v219
	v_mul_f32_e32 v68, v68, v131
	v_mul_f32_e32 v69, v69, v131
	v_mul_f32_e32 v70, v70, v131
	v_mul_f32_e32 v71, v71, v131
	v_mul_f32_e32 v72, v72, v131
	v_mul_f32_e32 v73, v73, v131
	v_mul_f32_e32 v74, v74, v131
	v_mul_f32_e32 v75, v75, v131
	v_fmac_f32_e32 v172, v68, v156
	v_fmac_f32_e32 v173, v69, v157
	v_fmac_f32_e32 v174, v70, v158
	v_fmac_f32_e32 v175, v71, v159
	v_fmac_f32_e32 v176, v72, v160
	v_fmac_f32_e32 v177, v73, v161
	v_fmac_f32_e32 v178, v74, v162
	v_fmac_f32_e32 v179, v75, v163
	v_fmac_f32_e32 v142, v172, v172
	v_fmac_f32_e32 v142, v173, v173
	v_fmac_f32_e32 v142, v174, v174
	v_fmac_f32_e32 v142, v175, v175
	v_fmac_f32_e32 v142, v176, v176
	v_fmac_f32_e32 v142, v177, v177
	v_fmac_f32_e32 v142, v178, v178
	v_fmac_f32_e32 v142, v179, v179
	v_cvt_pk_bf16_f32 v184, v172, v173
	v_cvt_pk_bf16_f32 v185, v174, v175
	v_cvt_pk_bf16_f32 v186, v176, v177
	v_cvt_pk_bf16_f32 v187, v178, v179
	global_store_dwordx4 v140, v[184:187], s[22:23] offset:256
	s_add_u32 s22, s60, 0x40000
	s_addc_u32 s23, s61, 0
	v_lshlrev_b32_e32 v164, 16, v220
	v_and_b32_e32 v165, 0xffff0000, v220
	v_lshlrev_b32_e32 v166, 16, v221
	v_and_b32_e32 v167, 0xffff0000, v221
	v_lshlrev_b32_e32 v168, 16, v222
	v_and_b32_e32 v169, 0xffff0000, v222
	v_lshlrev_b32_e32 v170, 16, v223
	v_and_b32_e32 v171, 0xffff0000, v223
	v_mul_f32_e32 v60, v60, v132
	v_mul_f32_e32 v61, v61, v132
	v_mul_f32_e32 v62, v62, v132
	v_mul_f32_e32 v63, v63, v132
	v_mul_f32_e32 v48, v48, v132
	v_mul_f32_e32 v49, v49, v132
	v_mul_f32_e32 v50, v50, v132
	v_mul_f32_e32 v51, v51, v132
	v_fmac_f32_e32 v164, v60, v148
	v_fmac_f32_e32 v165, v61, v149
	v_fmac_f32_e32 v166, v62, v150
	v_fmac_f32_e32 v167, v63, v151
	v_fmac_f32_e32 v168, v48, v152
	v_fmac_f32_e32 v169, v49, v153
	v_fmac_f32_e32 v170, v50, v154
	v_fmac_f32_e32 v171, v51, v155
	v_mul_f32_e32 v143, v164, v164
	v_fmac_f32_e32 v143, v165, v165
	v_fmac_f32_e32 v143, v166, v166
	v_fmac_f32_e32 v143, v167, v167
	v_fmac_f32_e32 v143, v168, v168
	v_fmac_f32_e32 v143, v169, v169
	v_fmac_f32_e32 v143, v170, v170
	v_fmac_f32_e32 v143, v171, v171
	v_cvt_pk_bf16_f32 v180, v164, v165
	v_cvt_pk_bf16_f32 v181, v166, v167
	v_cvt_pk_bf16_f32 v182, v168, v169
	v_cvt_pk_bf16_f32 v183, v170, v171
	global_store_dwordx4 v140, v[180:183], s[22:23]
	v_lshlrev_b32_e32 v172, 16, v224
	v_and_b32_e32 v173, 0xffff0000, v224
	v_lshlrev_b32_e32 v174, 16, v225
	v_and_b32_e32 v175, 0xffff0000, v225
	v_lshlrev_b32_e32 v176, 16, v226
	v_and_b32_e32 v177, 0xffff0000, v226
	v_lshlrev_b32_e32 v178, 16, v227
	v_and_b32_e32 v179, 0xffff0000, v227
	v_mul_f32_e32 v52, v52, v132
	v_mul_f32_e32 v53, v53, v132
	v_mul_f32_e32 v54, v54, v132
	v_mul_f32_e32 v55, v55, v132
	v_mul_f32_e32 v56, v56, v132
	v_mul_f32_e32 v57, v57, v132
	v_mul_f32_e32 v58, v58, v132
	v_mul_f32_e32 v59, v59, v132
	v_fmac_f32_e32 v172, v52, v156
	v_fmac_f32_e32 v173, v53, v157
	v_fmac_f32_e32 v174, v54, v158
	v_fmac_f32_e32 v175, v55, v159
	v_fmac_f32_e32 v176, v56, v160
	v_fmac_f32_e32 v177, v57, v161
	v_fmac_f32_e32 v178, v58, v162
	v_fmac_f32_e32 v179, v59, v163
	v_fmac_f32_e32 v143, v172, v172
	v_fmac_f32_e32 v143, v173, v173
	v_fmac_f32_e32 v143, v174, v174
	v_fmac_f32_e32 v143, v175, v175
	v_fmac_f32_e32 v143, v176, v176
	v_fmac_f32_e32 v143, v177, v177
	v_fmac_f32_e32 v143, v178, v178
	v_fmac_f32_e32 v143, v179, v179
	v_cvt_pk_bf16_f32 v184, v172, v173
	v_cvt_pk_bf16_f32 v185, v174, v175
	v_cvt_pk_bf16_f32 v186, v176, v177
	v_cvt_pk_bf16_f32 v187, v178, v179
	global_store_dwordx4 v140, v[184:187], s[22:23] offset:256
	s_add_u32 s22, s60, 0x48000
	s_addc_u32 s23, s61, 0
	v_lshlrev_b32_e32 v164, 16, v228
	v_and_b32_e32 v165, 0xffff0000, v228
	v_lshlrev_b32_e32 v166, 16, v229
	v_and_b32_e32 v167, 0xffff0000, v229
	v_lshlrev_b32_e32 v168, 16, v230
	v_and_b32_e32 v169, 0xffff0000, v230
	v_lshlrev_b32_e32 v170, 16, v231
	v_and_b32_e32 v171, 0xffff0000, v231
	v_mul_f32_e32 v44, v44, v133
	v_mul_f32_e32 v45, v45, v133
	v_mul_f32_e32 v46, v46, v133
	v_mul_f32_e32 v47, v47, v133
	v_mul_f32_e32 v32, v32, v133
	v_mul_f32_e32 v33, v33, v133
	v_mul_f32_e32 v34, v34, v133
	v_mul_f32_e32 v35, v35, v133
	v_fmac_f32_e32 v164, v44, v148
	v_fmac_f32_e32 v165, v45, v149
	v_fmac_f32_e32 v166, v46, v150
	v_fmac_f32_e32 v167, v47, v151
	v_fmac_f32_e32 v168, v32, v152
	v_fmac_f32_e32 v169, v33, v153
	v_fmac_f32_e32 v170, v34, v154
	v_fmac_f32_e32 v171, v35, v155
	v_mul_f32_e32 v144, v164, v164
	v_fmac_f32_e32 v144, v165, v165
	v_fmac_f32_e32 v144, v166, v166
	v_fmac_f32_e32 v144, v167, v167
	v_fmac_f32_e32 v144, v168, v168
	v_fmac_f32_e32 v144, v169, v169
	v_fmac_f32_e32 v144, v170, v170
	v_fmac_f32_e32 v144, v171, v171
	v_cvt_pk_bf16_f32 v180, v164, v165
	v_cvt_pk_bf16_f32 v181, v166, v167
	v_cvt_pk_bf16_f32 v182, v168, v169
	v_cvt_pk_bf16_f32 v183, v170, v171
	global_store_dwordx4 v140, v[180:183], s[22:23]
	v_lshlrev_b32_e32 v172, 16, v232
	v_and_b32_e32 v173, 0xffff0000, v232
	v_lshlrev_b32_e32 v174, 16, v233
	v_and_b32_e32 v175, 0xffff0000, v233
	v_lshlrev_b32_e32 v176, 16, v234
	v_and_b32_e32 v177, 0xffff0000, v234
	v_lshlrev_b32_e32 v178, 16, v235
	v_and_b32_e32 v179, 0xffff0000, v235
	v_mul_f32_e32 v36, v36, v133
	v_mul_f32_e32 v37, v37, v133
	v_mul_f32_e32 v38, v38, v133
	v_mul_f32_e32 v39, v39, v133
	v_mul_f32_e32 v40, v40, v133
	v_mul_f32_e32 v41, v41, v133
	v_mul_f32_e32 v42, v42, v133
	v_mul_f32_e32 v43, v43, v133
	v_fmac_f32_e32 v172, v36, v156
	v_fmac_f32_e32 v173, v37, v157
	v_fmac_f32_e32 v174, v38, v158
	v_fmac_f32_e32 v175, v39, v159
	v_fmac_f32_e32 v176, v40, v160
	v_fmac_f32_e32 v177, v41, v161
	v_fmac_f32_e32 v178, v42, v162
	v_fmac_f32_e32 v179, v43, v163
	v_fmac_f32_e32 v144, v172, v172
	v_fmac_f32_e32 v144, v173, v173
	v_fmac_f32_e32 v144, v174, v174
	v_fmac_f32_e32 v144, v175, v175
	v_fmac_f32_e32 v144, v176, v176
	v_fmac_f32_e32 v144, v177, v177
	v_fmac_f32_e32 v144, v178, v178
	v_fmac_f32_e32 v144, v179, v179
	v_cvt_pk_bf16_f32 v184, v172, v173
	v_cvt_pk_bf16_f32 v185, v174, v175
	v_cvt_pk_bf16_f32 v186, v176, v177
	v_cvt_pk_bf16_f32 v187, v178, v179
	global_store_dwordx4 v140, v[184:187], s[22:23] offset:256
	s_add_u32 s22, s60, 0x50000
	s_addc_u32 s23, s61, 0
	v_lshlrev_b32_e32 v164, 16, v236
	v_and_b32_e32 v165, 0xffff0000, v236
	v_lshlrev_b32_e32 v166, 16, v237
	v_and_b32_e32 v167, 0xffff0000, v237
	v_lshlrev_b32_e32 v168, 16, v238
	v_and_b32_e32 v169, 0xffff0000, v238
	v_lshlrev_b32_e32 v170, 16, v239
	v_and_b32_e32 v171, 0xffff0000, v239
	v_mul_f32_e32 v28, v28, v134
	v_mul_f32_e32 v29, v29, v134
	v_mul_f32_e32 v30, v30, v134
	v_mul_f32_e32 v31, v31, v134
	v_mul_f32_e32 v16, v16, v134
	v_mul_f32_e32 v17, v17, v134
	v_mul_f32_e32 v18, v18, v134
	v_mul_f32_e32 v19, v19, v134
	v_fmac_f32_e32 v164, v28, v148
	v_fmac_f32_e32 v165, v29, v149
	v_fmac_f32_e32 v166, v30, v150
	v_fmac_f32_e32 v167, v31, v151
	v_fmac_f32_e32 v168, v16, v152
	v_fmac_f32_e32 v169, v17, v153
	v_fmac_f32_e32 v170, v18, v154
	v_fmac_f32_e32 v171, v19, v155
	v_mul_f32_e32 v145, v164, v164
	v_fmac_f32_e32 v145, v165, v165
	v_fmac_f32_e32 v145, v166, v166
	v_fmac_f32_e32 v145, v167, v167
	v_fmac_f32_e32 v145, v168, v168
	v_fmac_f32_e32 v145, v169, v169
	v_fmac_f32_e32 v145, v170, v170
	v_fmac_f32_e32 v145, v171, v171
	v_cvt_pk_bf16_f32 v180, v164, v165
	v_cvt_pk_bf16_f32 v181, v166, v167
	v_cvt_pk_bf16_f32 v182, v168, v169
	v_cvt_pk_bf16_f32 v183, v170, v171
	global_store_dwordx4 v140, v[180:183], s[22:23]
	v_lshlrev_b32_e32 v172, 16, v240
	v_and_b32_e32 v173, 0xffff0000, v240
	v_lshlrev_b32_e32 v174, 16, v241
	v_and_b32_e32 v175, 0xffff0000, v241
	v_lshlrev_b32_e32 v176, 16, v242
	v_and_b32_e32 v177, 0xffff0000, v242
	v_lshlrev_b32_e32 v178, 16, v243
	v_and_b32_e32 v179, 0xffff0000, v243
	v_mul_f32_e32 v20, v20, v134
	v_mul_f32_e32 v21, v21, v134
	v_mul_f32_e32 v22, v22, v134
	v_mul_f32_e32 v23, v23, v134
	v_mul_f32_e32 v24, v24, v134
	v_mul_f32_e32 v25, v25, v134
	v_mul_f32_e32 v26, v26, v134
	v_mul_f32_e32 v27, v27, v134
	v_fmac_f32_e32 v172, v20, v156
	v_fmac_f32_e32 v173, v21, v157
	v_fmac_f32_e32 v174, v22, v158
	v_fmac_f32_e32 v175, v23, v159
	v_fmac_f32_e32 v176, v24, v160
	v_fmac_f32_e32 v177, v25, v161
	v_fmac_f32_e32 v178, v26, v162
	v_fmac_f32_e32 v179, v27, v163
	v_fmac_f32_e32 v145, v172, v172
	v_fmac_f32_e32 v145, v173, v173
	v_fmac_f32_e32 v145, v174, v174
	v_fmac_f32_e32 v145, v175, v175
	v_fmac_f32_e32 v145, v176, v176
	v_fmac_f32_e32 v145, v177, v177
	v_fmac_f32_e32 v145, v178, v178
	v_fmac_f32_e32 v145, v179, v179
	v_cvt_pk_bf16_f32 v184, v172, v173
	v_cvt_pk_bf16_f32 v185, v174, v175
	v_cvt_pk_bf16_f32 v186, v176, v177
	v_cvt_pk_bf16_f32 v187, v178, v179
	global_store_dwordx4 v140, v[184:187], s[22:23] offset:256
	s_add_u32 s22, s60, 0x58000
	s_addc_u32 s23, s61, 0
	v_lshlrev_b32_e32 v164, 16, v244
	v_and_b32_e32 v165, 0xffff0000, v244
	v_lshlrev_b32_e32 v166, 16, v245
	v_and_b32_e32 v167, 0xffff0000, v245
	v_lshlrev_b32_e32 v168, 16, v246
	v_and_b32_e32 v169, 0xffff0000, v246
	v_lshlrev_b32_e32 v170, 16, v247
	v_and_b32_e32 v171, 0xffff0000, v247
	v_mul_f32_e32 v12, v12, v135
	v_mul_f32_e32 v13, v13, v135
	v_mul_f32_e32 v14, v14, v135
	v_mul_f32_e32 v15, v15, v135
	v_mul_f32_e32 v0, v0, v135
	v_mul_f32_e32 v1, v1, v135
	v_mul_f32_e32 v2, v2, v135
	v_mul_f32_e32 v3, v3, v135
	v_fmac_f32_e32 v164, v12, v148
	v_fmac_f32_e32 v165, v13, v149
	v_fmac_f32_e32 v166, v14, v150
	v_fmac_f32_e32 v167, v15, v151
	v_fmac_f32_e32 v168, v0, v152
	v_fmac_f32_e32 v169, v1, v153
	v_fmac_f32_e32 v170, v2, v154
	v_fmac_f32_e32 v171, v3, v155
	v_mul_f32_e32 v146, v164, v164
	v_fmac_f32_e32 v146, v165, v165
	v_fmac_f32_e32 v146, v166, v166
	v_fmac_f32_e32 v146, v167, v167
	v_fmac_f32_e32 v146, v168, v168
	v_fmac_f32_e32 v146, v169, v169
	v_fmac_f32_e32 v146, v170, v170
	v_fmac_f32_e32 v146, v171, v171
	v_cvt_pk_bf16_f32 v180, v164, v165
	v_cvt_pk_bf16_f32 v181, v166, v167
	v_cvt_pk_bf16_f32 v182, v168, v169
	v_cvt_pk_bf16_f32 v183, v170, v171
	global_store_dwordx4 v140, v[180:183], s[22:23]
	v_lshlrev_b32_e32 v172, 16, v248
	v_and_b32_e32 v173, 0xffff0000, v248
	v_lshlrev_b32_e32 v174, 16, v249
	v_and_b32_e32 v175, 0xffff0000, v249
	v_lshlrev_b32_e32 v176, 16, v250
	v_and_b32_e32 v177, 0xffff0000, v250
	v_lshlrev_b32_e32 v178, 16, v251
	v_and_b32_e32 v179, 0xffff0000, v251
	v_mul_f32_e32 v4, v4, v135
	v_mul_f32_e32 v5, v5, v135
	v_mul_f32_e32 v6, v6, v135
	v_mul_f32_e32 v7, v7, v135
	v_mul_f32_e32 v8, v8, v135
	v_mul_f32_e32 v9, v9, v135
	v_mul_f32_e32 v10, v10, v135
	v_mul_f32_e32 v11, v11, v135
	v_fmac_f32_e32 v172, v4, v156
	v_fmac_f32_e32 v173, v5, v157
	v_fmac_f32_e32 v174, v6, v158
	v_fmac_f32_e32 v175, v7, v159
	v_fmac_f32_e32 v176, v8, v160
	v_fmac_f32_e32 v177, v9, v161
	v_fmac_f32_e32 v178, v10, v162
	v_fmac_f32_e32 v179, v11, v163
	v_fmac_f32_e32 v146, v172, v172
	v_fmac_f32_e32 v146, v173, v173
	v_fmac_f32_e32 v146, v174, v174
	v_fmac_f32_e32 v146, v175, v175
	v_fmac_f32_e32 v146, v176, v176
	v_fmac_f32_e32 v146, v177, v177
	v_fmac_f32_e32 v146, v178, v178
	v_fmac_f32_e32 v146, v179, v179
	v_cvt_pk_bf16_f32 v184, v172, v173
	v_cvt_pk_bf16_f32 v185, v174, v175
	v_cvt_pk_bf16_f32 v186, v176, v177
	v_cvt_pk_bf16_f32 v187, v178, v179
	global_store_dwordx4 v140, v[184:187], s[22:23] offset:256
	v_mov_b32_e32 v148, v138
	v_mov_b32_e32 v149, v139
	v_mov_b32_e32 v150, v141
	v_mov_b32_e32 v151, v142
	v_mov_b32_e32 v152, v143
	v_mov_b32_e32 v153, v144
	v_mov_b32_e32 v154, v145
	v_mov_b32_e32 v155, v146
	v_xor_b32_e32 v138, 16, v137
	v_xor_b32_e32 v139, 32, v137
	v_lshlrev_b32_e32 v138, 2, v138
	v_lshlrev_b32_e32 v139, 2, v139
	ds_bpermute_b32 v164, v138, v148
	ds_bpermute_b32 v165, v138, v149
	ds_bpermute_b32 v166, v138, v150
	ds_bpermute_b32 v167, v138, v151
	ds_bpermute_b32 v168, v138, v152
	ds_bpermute_b32 v169, v138, v153
	ds_bpermute_b32 v170, v138, v154
	ds_bpermute_b32 v171, v138, v155
	s_waitcnt lgkmcnt(0)
	v_add_f32_e32 v148, v148, v164
	v_add_f32_e32 v149, v149, v165
	v_add_f32_e32 v150, v150, v166
	v_add_f32_e32 v151, v151, v167
	v_add_f32_e32 v152, v152, v168
	v_add_f32_e32 v153, v153, v169
	v_add_f32_e32 v154, v154, v170
	v_add_f32_e32 v155, v155, v171
	ds_bpermute_b32 v164, v139, v148
	ds_bpermute_b32 v165, v139, v149
	ds_bpermute_b32 v166, v139, v150
	ds_bpermute_b32 v167, v139, v151
	ds_bpermute_b32 v168, v139, v152
	ds_bpermute_b32 v169, v139, v153
	ds_bpermute_b32 v170, v139, v154
	ds_bpermute_b32 v171, v139, v155
	s_waitcnt lgkmcnt(0)
	v_add_f32_e32 v148, v148, v164
	v_add_f32_e32 v149, v149, v165
	v_add_f32_e32 v150, v150, v166
	v_add_f32_e32 v151, v151, v167
	v_add_f32_e32 v152, v152, v168
	v_add_f32_e32 v153, v153, v169
	v_add_f32_e32 v154, v154, v170
	v_add_f32_e32 v155, v155, v171
	s_and_b32 s98, s2, 7
	s_lshl_b32 s98, s98, 3
	s_bfe_u32 s99, s2, 0x30003
	s_or_b32 s98, s98, s99
	s_lshr_b32 s99, s2, 6
	s_mul_i32 s99, s99, 0x42000
	s_lshl_b32 s98, s98, 10
	s_add_u32 s100, s56, s99
	s_addc_u32 s101, s57, 0
	s_add_u32 s100, s100, s98
	s_addc_u32 s101, s101, 0
	v_lshrrev_b32_e32 v158, 8, v136
	v_bfe_u32 v159, v136, 6, 2
	v_and_b32_e32 v160, 15, v136
	v_lshl_add_u32 v160, v158, 6, v160
	v_mul_u32_u24_e32 v159, 0x4200, v159
	v_add_u32_e32 v160, v160, v159
	v_lshlrev_b32_e32 v160, 2, v160
	v_bfe_u32 v161, v136, 4, 2
	v_cmp_eq_u32_e32 vcc, 0, v161
	s_and_saveexec_b64 s[0:1], vcc
	global_store_dword v160, v148, s[100:101]
	global_store_dword v160, v149, s[100:101] offset:64
	global_store_dword v160, v150, s[100:101] offset:128
	global_store_dword v160, v151, s[100:101] offset:192
	global_store_dword v160, v152, s[100:101] offset:512
	global_store_dword v160, v153, s[100:101] offset:576
	global_store_dword v160, v154, s[100:101] offset:640
	global_store_dword v160, v155, s[100:101] offset:704
	s_or_b64 exec, exec, s[0:1]
	v_bfe_u32 v183, v136, 1, 2
	v_lshrrev_b32_e32 v187, 6, v136
	v_lshlrev_b32_e32 v190, 11, v136
	v_lshrrev_b32_e32 v252, 1, v136
	v_and_b32_e32 v132, 48, v136
	v_and_b32_e32 v189, 63, v136
	v_lshrrev_b32_e32 v182, 3, v136
	v_lshlrev_b32_e32 v188, 2, v136
	v_lshl_add_u32 v186, v183, 6, 0
	v_and_b32_e32 v191, 15, v136
	s_cmpk_lt_i32 s2, 0x420
	v_mov_b32_e32 v0, v136
	s_cselect_b64 s[8:9], -1, 0
	s_cmpk_gt_i32 s2, 0x41f
	s_cbranch_scc1 .LBB0_863
	v_and_b32_e32 v4, 63, v0
	v_ashrrev_i32_e32 v0, 5, v0
	v_readlane_b32 s12, v253, 3
	v_and_b32_e32 v5, -2, v0
	v_lshlrev_b32_e32 v0, 4, v4
	v_mov_b32_e32 v1, 0
	v_readlane_b32 s13, v253, 4
	s_mov_b64 s[0:1], 0x1000
	v_readlane_b32 s14, v253, 5
	v_lshl_add_u64 v[2:3], s[12:13], 0, v[0:1]
	v_lshl_add_u64 v[16:17], v[2:3], 0, s[0:1]
	v_and_b32_e32 v2, 64, v137
	v_add_u32_e32 v2, 64, v2
	v_xor_b32_e32 v3, 32, v137
	v_cmp_lt_i32_e64 s[0:1], v3, v2
	v_readlane_b32 s15, v253, 6
	v_readlane_b32 s16, v253, 7
	v_cndmask_b32_e64 v3, v137, v3, s[0:1]
	v_lshlrev_b32_e32 v50, 2, v3
	v_xor_b32_e32 v3, 16, v137
	v_cmp_lt_i32_e64 s[0:1], v3, v2
	v_readlane_b32 s17, v253, 8
	v_readlane_b32 s18, v253, 9
	v_cndmask_b32_e64 v3, v137, v3, s[0:1]
	v_lshlrev_b32_e32 v51, 2, v3
	v_xor_b32_e32 v3, 8, v137
	v_cmp_lt_i32_e64 s[0:1], v3, v2
	v_readlane_b32 s19, v253, 10
	v_readlane_b32 s20, v253, 11
	v_cndmask_b32_e64 v3, v137, v3, s[0:1]
	v_lshlrev_b32_e32 v52, 2, v3
	v_xor_b32_e32 v3, 4, v137
	v_cmp_lt_i32_e64 s[0:1], v3, v2
	v_readlane_b32 s21, v253, 12
	v_readlane_b32 s22, v253, 13
	v_cndmask_b32_e64 v3, v137, v3, s[0:1]
	v_lshlrev_b32_e32 v53, 2, v3
	v_xor_b32_e32 v3, 2, v137
	v_cmp_lt_i32_e64 s[0:1], v3, v2
	v_readlane_b32 s23, v253, 14
	v_readlane_b32 s24, v253, 15
	v_cndmask_b32_e64 v3, v137, v3, s[0:1]
	v_readlane_b32 s25, v253, 16
	v_readlane_b32 s26, v253, 17
	v_readlane_b32 s27, v253, 18
	v_mul_u32_u24_e32 v0, 0x4200, v4
	v_lshlrev_b32_e32 v54, 2, v3
	v_xor_b32_e32 v3, 1, v137
	v_cmp_lt_i32_e64 s[0:1], v3, v2
	v_lshlrev_b32_e32 v0, 2, v0
	v_readlane_b32 s12, v253, 51
	v_cndmask_b32_e64 v2, v137, v3, s[0:1]
	v_lshl_add_u64 v[18:19], s[44:45], 0, v[0:1]
	v_lshlrev_b32_e32 v0, 3, v4
	v_readlane_b32 s13, v253, 52
	v_readlane_b32 s14, v253, 53
	v_readlane_b32 s15, v253, 54
	v_cmp_gt_u32_e32 vcc, 16, v4
	v_lshlrev_b32_e32 v55, 2, v2
	v_cmp_eq_u32_e64 s[0:1], 0, v4
	v_lshl_add_u64 v[20:21], s[60:61], 0, v[0:1]
	v_lshl_add_u64 v[22:23], s[14:15], 0, v[0:1]
	v_lshl_add_u64 v[24:25], s[58:59], 0, v[0:1]
	v_lshl_add_u32 v26, s2, 4, v5
	s_lshl_b32 s3, s38, 4
	v_mov_b32_e32 v56, 0x358637bd
	s_mov_b32 s12, 0x800000
	s_mov_b32 s13, s2
	v_readlane_b32 s16, v253, 55
	v_readlane_b32 s17, v253, 56
	v_readlane_b32 s18, v253, 57
	v_readlane_b32 s19, v253, 58
	v_readlane_b32 s20, v253, 59
	v_readlane_b32 s21, v253, 60
	v_readlane_b32 s22, v253, 61
	v_readlane_b32 s23, v253, 62
	v_readlane_b32 s24, v253, 63
	v_readlane_b32 s25, v254, 0
	v_readlane_b32 s26, v254, 1
	v_readlane_b32 s27, v254, 2
	s_addk_i32 s13, 0x400
	v_add_u32_e32 v26, 0x4000, v26
	s_cmpk_lt_i32 s13, 0x420
	s_cbranch_scc0 .LBB0_863
	s_branch .LBB0_855

.LBB0_1243:
	s_or_b64 exec, exec, s[0:1]
	s_waitcnt lgkmcnt(0)
	s_barrier
	s_and_b32 s98, s2, 7
	s_lshl_b32 s98, s98, 3
	s_bfe_u32 s99, s2, 0x30003
	s_or_b32 s98, s98, s99
	s_lshr_b32 s99, s2, 6
	v_and_b32_e32 v172, 0xff, v136
	v_lshrrev_b32_e32 v173, 8, v136
	v_mul_u32_u24_e32 v173, 0x84000, v173
	v_lshl_add_u32 v172, v172, 2, v173
	s_lshl_b32 s24, s98, 10
	s_add_u32 s18, s44, s24
	s_addc_u32 s19, s45, 0
	global_load_dword v164, v172, s[18:19]
	s_add_u32 s18, s18, 0x10800
	s_addc_u32 s19, s19, 0
	global_load_dword v165, v172, s[18:19]
	s_add_u32 s18, s18, 0x10800
	s_addc_u32 s19, s19, 0
	global_load_dword v166, v172, s[18:19]
	s_add_u32 s18, s18, 0x10800
	s_addc_u32 s19, s19, 0
	global_load_dword v167, v172, s[18:19]
	s_add_u32 s18, s18, 0x10800
	s_addc_u32 s19, s19, 0
	global_load_dword v168, v172, s[18:19]
	s_add_u32 s18, s18, 0x10800
	s_addc_u32 s19, s19, 0
	global_load_dword v169, v172, s[18:19]
	s_add_u32 s18, s18, 0x10800
	s_addc_u32 s19, s19, 0
	global_load_dword v170, v172, s[18:19]
	s_add_u32 s18, s18, 0x10800
	s_addc_u32 s19, s19, 0
	global_load_dword v171, v172, s[18:19]
	v_lshrrev_b32_e32 v141, 8, v136
	v_and_b32_e32 v142, 15, v136
	v_lshl_add_u32 v141, v141, 6, v142
	v_bfe_u32 v144, v136, 6, 2
	v_bfe_u32 v145, v136, 4, 2
	v_lshlrev_b32_e32 v144, 5, v144
	v_lshl_add_u32 v144, v145, 3, v144
	s_lshl_b32 s24, s99, 8
	v_add_u32_e32 v144, s24, v144
	s_lshl_b32 s25, s98, 8
	v_add_u32_e32 v145, s25, v141
	v_lshl_add_u32 v146, v145, 10, v144
	v_lshlrev_b32_e32 v140, 1, v146
	v_lshlrev_b32_e32 v147, 2, v144
	v_readlane_b32 s18, v253, 3
	v_readlane_b32 s19, v253, 4
	s_mov_b32 s20, s60
	s_mov_b32 s21, s61
	s_nop 4
	s_add_u32 s18, s18, 0x3000
	s_addc_u32 s19, s19, 0
	global_load_dwordx4 v[148:151], v147, s[18:19]
	global_load_dwordx4 v[152:155], v147, s[18:19] offset:16
	global_load_dwordx4 v[156:159], v147, s[18:19] offset:512
	global_load_dwordx4 v[160:163], v147, s[18:19] offset:528
	s_add_u32 s22, s20, 0x0
	s_addc_u32 s23, s21, 0
	global_load_dwordx4 v[188:191], v140, s[22:23] nt
	global_load_dwordx4 v[192:195], v140, s[22:23] offset:256 nt
	s_add_u32 s22, s20, 0x8000
	s_addc_u32 s23, s21, 0
	global_load_dwordx4 v[196:199], v140, s[22:23] nt
	global_load_dwordx4 v[200:203], v140, s[22:23] offset:256 nt
	s_add_u32 s22, s20, 0x10000
	s_addc_u32 s23, s21, 0
	global_load_dwordx4 v[204:207], v140, s[22:23] nt
	global_load_dwordx4 v[208:211], v140, s[22:23] offset:256 nt
	s_add_u32 s22, s20, 0x18000
	s_addc_u32 s23, s21, 0
	global_load_dwordx4 v[212:215], v140, s[22:23] nt
	global_load_dwordx4 v[216:219], v140, s[22:23] offset:256 nt
	s_add_u32 s22, s20, 0x40000
	s_addc_u32 s23, s21, 0
	global_load_dwordx4 v[220:223], v140, s[22:23] nt
	global_load_dwordx4 v[224:227], v140, s[22:23] offset:256 nt
	s_add_u32 s22, s20, 0x48000
	s_addc_u32 s23, s21, 0
	global_load_dwordx4 v[228:231], v140, s[22:23] nt
	global_load_dwordx4 v[232:235], v140, s[22:23] offset:256 nt
	s_add_u32 s22, s20, 0x50000
	s_addc_u32 s23, s21, 0
	global_load_dwordx4 v[236:239], v140, s[22:23] nt
	global_load_dwordx4 v[240:243], v140, s[22:23] offset:256 nt
	s_add_u32 s22, s20, 0x58000
	s_addc_u32 s23, s21, 0
	global_load_dwordx4 v[244:247], v140, s[22:23] nt
	global_load_dwordx4 v[248:251], v140, s[22:23] offset:256 nt
	s_cmp_lt_u32 s2, 32
	s_cbranch_scc0 .Ltouch_1
	v_and_b32_e32 v185, 63, v136
	v_lshrrev_b32_e32 v186, 6, v136
	s_lshl_b32 s24, s2, 4
	s_add_i32 s24, s24, 0x4000
	v_lshl_add_u32 v186, v186, 1, s24
	v_lshlrev_b32_e32 v187, 11, v186
	v_lshl_add_u32 v187, v185, 6, v187
	global_load_dword v184, v187, s[20:21]
	global_load_dword v184, v187, s[58:59]
	v_and_b32_e32 v185, 15, v185
	v_mul_u32_u24_e32 v185, 0x10800, v185
	v_lshl_add_u32 v185, v186, 2, v185
	global_load_dword v184, v185, s[44:45]
.Ltouch_1:
	s_waitcnt vmcnt(20)
	v_add_f32_e32 v164, v164, v165
	v_add_f32_e32 v164, v164, v166
	v_add_f32_e32 v164, v164, v167
	v_add_f32_e32 v164, v164, v168
	v_add_f32_e32 v164, v164, v169
	v_add_f32_e32 v164, v164, v170
	v_add_f32_e32 v164, v164, v171
	v_lshlrev_b32_e32 v173, 2, v136
	ds_write_b32 v173, v164
	s_waitcnt lgkmcnt(0)
	s_barrier
	v_lshlrev_b32_e32 v142, 2, v141
	ds_read_b32 v128, v142 offset:0
	ds_read_b32 v174, v142 offset:1024
	ds_read_b32 v129, v142 offset:64
	ds_read_b32 v175, v142 offset:1088
	ds_read_b32 v130, v142 offset:128
	ds_read_b32 v176, v142 offset:1152
	ds_read_b32 v131, v142 offset:192
	ds_read_b32 v177, v142 offset:1216
	ds_read_b32 v132, v142 offset:512
	ds_read_b32 v178, v142 offset:1536
	ds_read_b32 v133, v142 offset:576
	ds_read_b32 v179, v142 offset:1600
	ds_read_b32 v134, v142 offset:640
	ds_read_b32 v180, v142 offset:1664
	ds_read_b32 v135, v142 offset:704
	ds_read_b32 v181, v142 offset:1728
	s_waitcnt lgkmcnt(0)
	s_mov_b32 s101, 0x3a800000
	v_mov_b32_e32 v143, 0x358637bd
	v_add_f32_e32 v128, v128, v174
	v_add_f32_e32 v129, v129, v175
	v_add_f32_e32 v130, v130, v176
	v_add_f32_e32 v131, v131, v177
	v_add_f32_e32 v132, v132, v178
	v_add_f32_e32 v133, v133, v179
	v_add_f32_e32 v134, v134, v180
	v_add_f32_e32 v135, v135, v181
	v_fma_f32 v128, v128, s101, v143
	v_fma_f32 v129, v129, s101, v143
	v_fma_f32 v130, v130, s101, v143
	v_fma_f32 v131, v131, s101, v143
	v_fma_f32 v132, v132, s101, v143
	v_fma_f32 v133, v133, s101, v143
	v_fma_f32 v134, v134, s101, v143
	v_fma_f32 v135, v135, s101, v143
	v_rsq_f32_e32 v128, v128
	v_rsq_f32_e32 v129, v129
	v_rsq_f32_e32 v130, v130
	v_rsq_f32_e32 v131, v131
	v_rsq_f32_e32 v132, v132
	v_rsq_f32_e32 v133, v133
	v_rsq_f32_e32 v134, v134
	v_rsq_f32_e32 v135, v135
	s_waitcnt vmcnt(0)
	s_add_u32 s22, s64, 0x0
	s_addc_u32 s23, s65, 0
	v_lshlrev_b32_e32 v164, 16, v188
	v_and_b32_e32 v165, 0xffff0000, v188
	v_lshlrev_b32_e32 v166, 16, v189
	v_and_b32_e32 v167, 0xffff0000, v189
	v_lshlrev_b32_e32 v168, 16, v190
	v_and_b32_e32 v169, 0xffff0000, v190
	v_lshlrev_b32_e32 v170, 16, v191
	v_and_b32_e32 v171, 0xffff0000, v191
	v_mul_f32_e32 v124, v124, v128
	v_mul_f32_e32 v125, v125, v128
	v_mul_f32_e32 v126, v126, v128
	v_mul_f32_e32 v127, v127, v128
	v_mul_f32_e32 v112, v112, v128
	v_mul_f32_e32 v113, v113, v128
	v_mul_f32_e32 v114, v114, v128
	v_mul_f32_e32 v115, v115, v128
	v_fmac_f32_e32 v164, v124, v148
	v_fmac_f32_e32 v165, v125, v149
	v_fmac_f32_e32 v166, v126, v150
	v_fmac_f32_e32 v167, v127, v151
	v_fmac_f32_e32 v168, v112, v152
	v_fmac_f32_e32 v169, v113, v153
	v_fmac_f32_e32 v170, v114, v154
	v_fmac_f32_e32 v171, v115, v155
	v_mul_f32_e32 v138, v164, v164
	v_fmac_f32_e32 v138, v165, v165
	v_fmac_f32_e32 v138, v166, v166
	v_fmac_f32_e32 v138, v167, v167
	v_fmac_f32_e32 v138, v168, v168
	v_fmac_f32_e32 v138, v169, v169
	v_fmac_f32_e32 v138, v170, v170
	v_fmac_f32_e32 v138, v171, v171
	v_cvt_pk_bf16_f32 v180, v164, v165
	v_cvt_pk_bf16_f32 v181, v166, v167
	v_cvt_pk_bf16_f32 v182, v168, v169
	v_cvt_pk_bf16_f32 v183, v170, v171
	global_store_dwordx4 v140, v[180:183], s[22:23]
	v_lshlrev_b32_e32 v172, 16, v192
	v_and_b32_e32 v173, 0xffff0000, v192
	v_lshlrev_b32_e32 v174, 16, v193
	v_and_b32_e32 v175, 0xffff0000, v193
	v_lshlrev_b32_e32 v176, 16, v194
	v_and_b32_e32 v177, 0xffff0000, v194
	v_lshlrev_b32_e32 v178, 16, v195
	v_and_b32_e32 v179, 0xffff0000, v195
	v_mul_f32_e32 v120, v120, v128
	v_mul_f32_e32 v121, v121, v128
	v_mul_f32_e32 v122, v122, v128
	v_mul_f32_e32 v123, v123, v128
	v_mul_f32_e32 v116, v116, v128
	v_mul_f32_e32 v117, v117, v128
	v_mul_f32_e32 v118, v118, v128
	v_mul_f32_e32 v119, v119, v128
	v_fmac_f32_e32 v172, v120, v156
	v_fmac_f32_e32 v173, v121, v157
	v_fmac_f32_e32 v174, v122, v158
	v_fmac_f32_e32 v175, v123, v159
	v_fmac_f32_e32 v176, v116, v160
	v_fmac_f32_e32 v177, v117, v161
	v_fmac_f32_e32 v178, v118, v162
	v_fmac_f32_e32 v179, v119, v163
	v_fmac_f32_e32 v138, v172, v172
	v_fmac_f32_e32 v138, v173, v173
	v_fmac_f32_e32 v138, v174, v174
	v_fmac_f32_e32 v138, v175, v175
	v_fmac_f32_e32 v138, v176, v176
	v_fmac_f32_e32 v138, v177, v177
	v_fmac_f32_e32 v138, v178, v178
	v_fmac_f32_e32 v138, v179, v179
	v_cvt_pk_bf16_f32 v184, v172, v173
	v_cvt_pk_bf16_f32 v185, v174, v175
	v_cvt_pk_bf16_f32 v186, v176, v177
	v_cvt_pk_bf16_f32 v187, v178, v179
	global_store_dwordx4 v140, v[184:187], s[22:23] offset:256
	s_add_u32 s22, s64, 0x8000
	s_addc_u32 s23, s65, 0
	v_lshlrev_b32_e32 v164, 16, v196
	v_and_b32_e32 v165, 0xffff0000, v196
	v_lshlrev_b32_e32 v166, 16, v197
	v_and_b32_e32 v167, 0xffff0000, v197
	v_lshlrev_b32_e32 v168, 16, v198
	v_and_b32_e32 v169, 0xffff0000, v198
	v_lshlrev_b32_e32 v170, 16, v199
	v_and_b32_e32 v171, 0xffff0000, v199
	v_mul_f32_e32 v108, v108, v129
	v_mul_f32_e32 v109, v109, v129
	v_mul_f32_e32 v110, v110, v129
	v_mul_f32_e32 v111, v111, v129
	v_mul_f32_e32 v96, v96, v129
	v_mul_f32_e32 v97, v97, v129
	v_mul_f32_e32 v98, v98, v129
	v_mul_f32_e32 v99, v99, v129
	v_fmac_f32_e32 v164, v108, v148
	v_fmac_f32_e32 v165, v109, v149
	v_fmac_f32_e32 v166, v110, v150
	v_fmac_f32_e32 v167, v111, v151
	v_fmac_f32_e32 v168, v96, v152
	v_fmac_f32_e32 v169, v97, v153
	v_fmac_f32_e32 v170, v98, v154
	v_fmac_f32_e32 v171, v99, v155
	v_mul_f32_e32 v139, v164, v164
	v_fmac_f32_e32 v139, v165, v165
	v_fmac_f32_e32 v139, v166, v166
	v_fmac_f32_e32 v139, v167, v167
	v_fmac_f32_e32 v139, v168, v168
	v_fmac_f32_e32 v139, v169, v169
	v_fmac_f32_e32 v139, v170, v170
	v_fmac_f32_e32 v139, v171, v171
	v_cvt_pk_bf16_f32 v180, v164, v165
	v_cvt_pk_bf16_f32 v181, v166, v167
	v_cvt_pk_bf16_f32 v182, v168, v169
	v_cvt_pk_bf16_f32 v183, v170, v171
	global_store_dwordx4 v140, v[180:183], s[22:23]
	v_lshlrev_b32_e32 v172, 16, v200
	v_and_b32_e32 v173, 0xffff0000, v200
	v_lshlrev_b32_e32 v174, 16, v201
	v_and_b32_e32 v175, 0xffff0000, v201
	v_lshlrev_b32_e32 v176, 16, v202
	v_and_b32_e32 v177, 0xffff0000, v202
	v_lshlrev_b32_e32 v178, 16, v203
	v_and_b32_e32 v179, 0xffff0000, v203
	v_mul_f32_e32 v100, v100, v129
	v_mul_f32_e32 v101, v101, v129
	v_mul_f32_e32 v102, v102, v129
	v_mul_f32_e32 v103, v103, v129
	v_mul_f32_e32 v104, v104, v129
	v_mul_f32_e32 v105, v105, v129
	v_mul_f32_e32 v106, v106, v129
	v_mul_f32_e32 v107, v107, v129
	v_fmac_f32_e32 v172, v100, v156
	v_fmac_f32_e32 v173, v101, v157
	v_fmac_f32_e32 v174, v102, v158
	v_fmac_f32_e32 v175, v103, v159
	v_fmac_f32_e32 v176, v104, v160
	v_fmac_f32_e32 v177, v105, v161
	v_fmac_f32_e32 v178, v106, v162
	v_fmac_f32_e32 v179, v107, v163
	v_fmac_f32_e32 v139, v172, v172
	v_fmac_f32_e32 v139, v173, v173
	v_fmac_f32_e32 v139, v174, v174
	v_fmac_f32_e32 v139, v175, v175
	v_fmac_f32_e32 v139, v176, v176
	v_fmac_f32_e32 v139, v177, v177
	v_fmac_f32_e32 v139, v178, v178
	v_fmac_f32_e32 v139, v179, v179
	v_cvt_pk_bf16_f32 v184, v172, v173
	v_cvt_pk_bf16_f32 v185, v174, v175
	v_cvt_pk_bf16_f32 v186, v176, v177
	v_cvt_pk_bf16_f32 v187, v178, v179
	global_store_dwordx4 v140, v[184:187], s[22:23] offset:256
	s_add_u32 s22, s64, 0x10000
	s_addc_u32 s23, s65, 0
	v_lshlrev_b32_e32 v164, 16, v204
	v_and_b32_e32 v165, 0xffff0000, v204
	v_lshlrev_b32_e32 v166, 16, v205
	v_and_b32_e32 v167, 0xffff0000, v205
	v_lshlrev_b32_e32 v168, 16, v206
	v_and_b32_e32 v169, 0xffff0000, v206
	v_lshlrev_b32_e32 v170, 16, v207
	v_and_b32_e32 v171, 0xffff0000, v207
	v_mul_f32_e32 v92, v92, v130
	v_mul_f32_e32 v93, v93, v130
	v_mul_f32_e32 v94, v94, v130
	v_mul_f32_e32 v95, v95, v130
	v_mul_f32_e32 v80, v80, v130
	v_mul_f32_e32 v81, v81, v130
	v_mul_f32_e32 v82, v82, v130
	v_mul_f32_e32 v83, v83, v130
	v_fmac_f32_e32 v164, v92, v148
	v_fmac_f32_e32 v165, v93, v149
	v_fmac_f32_e32 v166, v94, v150
	v_fmac_f32_e32 v167, v95, v151
	v_fmac_f32_e32 v168, v80, v152
	v_fmac_f32_e32 v169, v81, v153
	v_fmac_f32_e32 v170, v82, v154
	v_fmac_f32_e32 v171, v83, v155
	v_mul_f32_e32 v141, v164, v164
	v_fmac_f32_e32 v141, v165, v165
	v_fmac_f32_e32 v141, v166, v166
	v_fmac_f32_e32 v141, v167, v167
	v_fmac_f32_e32 v141, v168, v168
	v_fmac_f32_e32 v141, v169, v169
	v_fmac_f32_e32 v141, v170, v170
	v_fmac_f32_e32 v141, v171, v171
	v_cvt_pk_bf16_f32 v180, v164, v165
	v_cvt_pk_bf16_f32 v181, v166, v167
	v_cvt_pk_bf16_f32 v182, v168, v169
	v_cvt_pk_bf16_f32 v183, v170, v171
	global_store_dwordx4 v140, v[180:183], s[22:23]
	v_lshlrev_b32_e32 v172, 16, v208
	v_and_b32_e32 v173, 0xffff0000, v208
	v_lshlrev_b32_e32 v174, 16, v209
	v_and_b32_e32 v175, 0xffff0000, v209
	v_lshlrev_b32_e32 v176, 16, v210
	v_and_b32_e32 v177, 0xffff0000, v210
	v_lshlrev_b32_e32 v178, 16, v211
	v_and_b32_e32 v179, 0xffff0000, v211
	v_mul_f32_e32 v84, v84, v130
	v_mul_f32_e32 v85, v85, v130
	v_mul_f32_e32 v86, v86, v130
	v_mul_f32_e32 v87, v87, v130
	v_mul_f32_e32 v88, v88, v130
	v_mul_f32_e32 v89, v89, v130
	v_mul_f32_e32 v90, v90, v130
	v_mul_f32_e32 v91, v91, v130
	v_fmac_f32_e32 v172, v84, v156
	v_fmac_f32_e32 v173, v85, v157
	v_fmac_f32_e32 v174, v86, v158
	v_fmac_f32_e32 v175, v87, v159
	v_fmac_f32_e32 v176, v88, v160
	v_fmac_f32_e32 v177, v89, v161
	v_fmac_f32_e32 v178, v90, v162
	v_fmac_f32_e32 v179, v91, v163
	v_fmac_f32_e32 v141, v172, v172
	v_fmac_f32_e32 v141, v173, v173
	v_fmac_f32_e32 v141, v174, v174
	v_fmac_f32_e32 v141, v175, v175
	v_fmac_f32_e32 v141, v176, v176
	v_fmac_f32_e32 v141, v177, v177
	v_fmac_f32_e32 v141, v178, v178
	v_fmac_f32_e32 v141, v179, v179
	v_cvt_pk_bf16_f32 v184, v172, v173
	v_cvt_pk_bf16_f32 v185, v174, v175
	v_cvt_pk_bf16_f32 v186, v176, v177
	v_cvt_pk_bf16_f32 v187, v178, v179
	global_store_dwordx4 v140, v[184:187], s[22:23] offset:256
	s_add_u32 s22, s64, 0x18000
	s_addc_u32 s23, s65, 0
	v_lshlrev_b32_e32 v164, 16, v212
	v_and_b32_e32 v165, 0xffff0000, v212
	v_lshlrev_b32_e32 v166, 16, v213
	v_and_b32_e32 v167, 0xffff0000, v213
	v_lshlrev_b32_e32 v168, 16, v214
	v_and_b32_e32 v169, 0xffff0000, v214
	v_lshlrev_b32_e32 v170, 16, v215
	v_and_b32_e32 v171, 0xffff0000, v215
	v_mul_f32_e32 v76, v76, v131
	v_mul_f32_e32 v77, v77, v131
	v_mul_f32_e32 v78, v78, v131
	v_mul_f32_e32 v79, v79, v131
	v_mul_f32_e32 v64, v64, v131
	v_mul_f32_e32 v65, v65, v131
	v_mul_f32_e32 v66, v66, v131
	v_mul_f32_e32 v67, v67, v131
	v_fmac_f32_e32 v164, v76, v148
	v_fmac_f32_e32 v165, v77, v149
	v_fmac_f32_e32 v166, v78, v150
	v_fmac_f32_e32 v167, v79, v151
	v_fmac_f32_e32 v168, v64, v152
	v_fmac_f32_e32 v169, v65, v153
	v_fmac_f32_e32 v170, v66, v154
	v_fmac_f32_e32 v171, v67, v155
	v_mul_f32_e32 v142, v164, v164
	v_fmac_f32_e32 v142, v165, v165
	v_fmac_f32_e32 v142, v166, v166
	v_fmac_f32_e32 v142, v167, v167
	v_fmac_f32_e32 v142, v168, v168
	v_fmac_f32_e32 v142, v169, v169
	v_fmac_f32_e32 v142, v170, v170
	v_fmac_f32_e32 v142, v171, v171
	v_cvt_pk_bf16_f32 v180, v164, v165
	v_cvt_pk_bf16_f32 v181, v166, v167
	v_cvt_pk_bf16_f32 v182, v168, v169
	v_cvt_pk_bf16_f32 v183, v170, v171
	global_store_dwordx4 v140, v[180:183], s[22:23]
	v_lshlrev_b32_e32 v172, 16, v216
	v_and_b32_e32 v173, 0xffff0000, v216
	v_lshlrev_b32_e32 v174, 16, v217
	v_and_b32_e32 v175, 0xffff0000, v217
	v_lshlrev_b32_e32 v176, 16, v218
	v_and_b32_e32 v177, 0xffff0000, v218
	v_lshlrev_b32_e32 v178, 16, v219
	v_and_b32_e32 v179, 0xffff0000, v219
	v_mul_f32_e32 v68, v68, v131
	v_mul_f32_e32 v69, v69, v131
	v_mul_f32_e32 v70, v70, v131
	v_mul_f32_e32 v71, v71, v131
	v_mul_f32_e32 v72, v72, v131
	v_mul_f32_e32 v73, v73, v131
	v_mul_f32_e32 v74, v74, v131
	v_mul_f32_e32 v75, v75, v131
	v_fmac_f32_e32 v172, v68, v156
	v_fmac_f32_e32 v173, v69, v157
	v_fmac_f32_e32 v174, v70, v158
	v_fmac_f32_e32 v175, v71, v159
	v_fmac_f32_e32 v176, v72, v160
	v_fmac_f32_e32 v177, v73, v161
	v_fmac_f32_e32 v178, v74, v162
	v_fmac_f32_e32 v179, v75, v163
	v_fmac_f32_e32 v142, v172, v172
	v_fmac_f32_e32 v142, v173, v173
	v_fmac_f32_e32 v142, v174, v174
	v_fmac_f32_e32 v142, v175, v175
	v_fmac_f32_e32 v142, v176, v176
	v_fmac_f32_e32 v142, v177, v177
	v_fmac_f32_e32 v142, v178, v178
	v_fmac_f32_e32 v142, v179, v179
	v_cvt_pk_bf16_f32 v184, v172, v173
	v_cvt_pk_bf16_f32 v185, v174, v175
	v_cvt_pk_bf16_f32 v186, v176, v177
	v_cvt_pk_bf16_f32 v187, v178, v179
	global_store_dwordx4 v140, v[184:187], s[22:23] offset:256
	s_add_u32 s22, s64, 0x40000
	s_addc_u32 s23, s65, 0
	v_lshlrev_b32_e32 v164, 16, v220
	v_and_b32_e32 v165, 0xffff0000, v220
	v_lshlrev_b32_e32 v166, 16, v221
	v_and_b32_e32 v167, 0xffff0000, v221
	v_lshlrev_b32_e32 v168, 16, v222
	v_and_b32_e32 v169, 0xffff0000, v222
	v_lshlrev_b32_e32 v170, 16, v223
	v_and_b32_e32 v171, 0xffff0000, v223
	v_mul_f32_e32 v60, v60, v132
	v_mul_f32_e32 v61, v61, v132
	v_mul_f32_e32 v62, v62, v132
	v_mul_f32_e32 v63, v63, v132
	v_mul_f32_e32 v48, v48, v132
	v_mul_f32_e32 v49, v49, v132
	v_mul_f32_e32 v50, v50, v132
	v_mul_f32_e32 v51, v51, v132
	v_fmac_f32_e32 v164, v60, v148
	v_fmac_f32_e32 v165, v61, v149
	v_fmac_f32_e32 v166, v62, v150
	v_fmac_f32_e32 v167, v63, v151
	v_fmac_f32_e32 v168, v48, v152
	v_fmac_f32_e32 v169, v49, v153
	v_fmac_f32_e32 v170, v50, v154
	v_fmac_f32_e32 v171, v51, v155
	v_mul_f32_e32 v143, v164, v164
	v_fmac_f32_e32 v143, v165, v165
	v_fmac_f32_e32 v143, v166, v166
	v_fmac_f32_e32 v143, v167, v167
	v_fmac_f32_e32 v143, v168, v168
	v_fmac_f32_e32 v143, v169, v169
	v_fmac_f32_e32 v143, v170, v170
	v_fmac_f32_e32 v143, v171, v171
	v_cvt_pk_bf16_f32 v180, v164, v165
	v_cvt_pk_bf16_f32 v181, v166, v167
	v_cvt_pk_bf16_f32 v182, v168, v169
	v_cvt_pk_bf16_f32 v183, v170, v171
	global_store_dwordx4 v140, v[180:183], s[22:23]
	v_lshlrev_b32_e32 v172, 16, v224
	v_and_b32_e32 v173, 0xffff0000, v224
	v_lshlrev_b32_e32 v174, 16, v225
	v_and_b32_e32 v175, 0xffff0000, v225
	v_lshlrev_b32_e32 v176, 16, v226
	v_and_b32_e32 v177, 0xffff0000, v226
	v_lshlrev_b32_e32 v178, 16, v227
	v_and_b32_e32 v179, 0xffff0000, v227
	v_mul_f32_e32 v52, v52, v132
	v_mul_f32_e32 v53, v53, v132
	v_mul_f32_e32 v54, v54, v132
	v_mul_f32_e32 v55, v55, v132
	v_mul_f32_e32 v56, v56, v132
	v_mul_f32_e32 v57, v57, v132
	v_mul_f32_e32 v58, v58, v132
	v_mul_f32_e32 v59, v59, v132
	v_fmac_f32_e32 v172, v52, v156
	v_fmac_f32_e32 v173, v53, v157
	v_fmac_f32_e32 v174, v54, v158
	v_fmac_f32_e32 v175, v55, v159
	v_fmac_f32_e32 v176, v56, v160
	v_fmac_f32_e32 v177, v57, v161
	v_fmac_f32_e32 v178, v58, v162
	v_fmac_f32_e32 v179, v59, v163
	v_fmac_f32_e32 v143, v172, v172
	v_fmac_f32_e32 v143, v173, v173
	v_fmac_f32_e32 v143, v174, v174
	v_fmac_f32_e32 v143, v175, v175
	v_fmac_f32_e32 v143, v176, v176
	v_fmac_f32_e32 v143, v177, v177
	v_fmac_f32_e32 v143, v178, v178
	v_fmac_f32_e32 v143, v179, v179
	v_cvt_pk_bf16_f32 v184, v172, v173
	v_cvt_pk_bf16_f32 v185, v174, v175
	v_cvt_pk_bf16_f32 v186, v176, v177
	v_cvt_pk_bf16_f32 v187, v178, v179
	global_store_dwordx4 v140, v[184:187], s[22:23] offset:256
	s_add_u32 s22, s64, 0x48000
	s_addc_u32 s23, s65, 0
	v_lshlrev_b32_e32 v164, 16, v228
	v_and_b32_e32 v165, 0xffff0000, v228
	v_lshlrev_b32_e32 v166, 16, v229
	v_and_b32_e32 v167, 0xffff0000, v229
	v_lshlrev_b32_e32 v168, 16, v230
	v_and_b32_e32 v169, 0xffff0000, v230
	v_lshlrev_b32_e32 v170, 16, v231
	v_and_b32_e32 v171, 0xffff0000, v231
	v_mul_f32_e32 v44, v44, v133
	v_mul_f32_e32 v45, v45, v133
	v_mul_f32_e32 v46, v46, v133
	v_mul_f32_e32 v47, v47, v133
	v_mul_f32_e32 v32, v32, v133
	v_mul_f32_e32 v33, v33, v133
	v_mul_f32_e32 v34, v34, v133
	v_mul_f32_e32 v35, v35, v133
	v_fmac_f32_e32 v164, v44, v148
	v_fmac_f32_e32 v165, v45, v149
	v_fmac_f32_e32 v166, v46, v150
	v_fmac_f32_e32 v167, v47, v151
	v_fmac_f32_e32 v168, v32, v152
	v_fmac_f32_e32 v169, v33, v153
	v_fmac_f32_e32 v170, v34, v154
	v_fmac_f32_e32 v171, v35, v155
	v_mul_f32_e32 v144, v164, v164
	v_fmac_f32_e32 v144, v165, v165
	v_fmac_f32_e32 v144, v166, v166
	v_fmac_f32_e32 v144, v167, v167
	v_fmac_f32_e32 v144, v168, v168
	v_fmac_f32_e32 v144, v169, v169
	v_fmac_f32_e32 v144, v170, v170
	v_fmac_f32_e32 v144, v171, v171
	v_cvt_pk_bf16_f32 v180, v164, v165
	v_cvt_pk_bf16_f32 v181, v166, v167
	v_cvt_pk_bf16_f32 v182, v168, v169
	v_cvt_pk_bf16_f32 v183, v170, v171
	global_store_dwordx4 v140, v[180:183], s[22:23]
	v_lshlrev_b32_e32 v172, 16, v232
	v_and_b32_e32 v173, 0xffff0000, v232
	v_lshlrev_b32_e32 v174, 16, v233
	v_and_b32_e32 v175, 0xffff0000, v233
	v_lshlrev_b32_e32 v176, 16, v234
	v_and_b32_e32 v177, 0xffff0000, v234
	v_lshlrev_b32_e32 v178, 16, v235
	v_and_b32_e32 v179, 0xffff0000, v235
	v_mul_f32_e32 v36, v36, v133
	v_mul_f32_e32 v37, v37, v133
	v_mul_f32_e32 v38, v38, v133
	v_mul_f32_e32 v39, v39, v133
	v_mul_f32_e32 v40, v40, v133
	v_mul_f32_e32 v41, v41, v133
	v_mul_f32_e32 v42, v42, v133
	v_mul_f32_e32 v43, v43, v133
	v_fmac_f32_e32 v172, v36, v156
	v_fmac_f32_e32 v173, v37, v157
	v_fmac_f32_e32 v174, v38, v158
	v_fmac_f32_e32 v175, v39, v159
	v_fmac_f32_e32 v176, v40, v160
	v_fmac_f32_e32 v177, v41, v161
	v_fmac_f32_e32 v178, v42, v162
	v_fmac_f32_e32 v179, v43, v163
	v_fmac_f32_e32 v144, v172, v172
	v_fmac_f32_e32 v144, v173, v173
	v_fmac_f32_e32 v144, v174, v174
	v_fmac_f32_e32 v144, v175, v175
	v_fmac_f32_e32 v144, v176, v176
	v_fmac_f32_e32 v144, v177, v177
	v_fmac_f32_e32 v144, v178, v178
	v_fmac_f32_e32 v144, v179, v179
	v_cvt_pk_bf16_f32 v184, v172, v173
	v_cvt_pk_bf16_f32 v185, v174, v175
	v_cvt_pk_bf16_f32 v186, v176, v177
	v_cvt_pk_bf16_f32 v187, v178, v179
	global_store_dwordx4 v140, v[184:187], s[22:23] offset:256
	s_add_u32 s22, s64, 0x50000
	s_addc_u32 s23, s65, 0
	v_lshlrev_b32_e32 v164, 16, v236
	v_and_b32_e32 v165, 0xffff0000, v236
	v_lshlrev_b32_e32 v166, 16, v237
	v_and_b32_e32 v167, 0xffff0000, v237
	v_lshlrev_b32_e32 v168, 16, v238
	v_and_b32_e32 v169, 0xffff0000, v238
	v_lshlrev_b32_e32 v170, 16, v239
	v_and_b32_e32 v171, 0xffff0000, v239
	v_mul_f32_e32 v28, v28, v134
	v_mul_f32_e32 v29, v29, v134
	v_mul_f32_e32 v30, v30, v134
	v_mul_f32_e32 v31, v31, v134
	v_mul_f32_e32 v16, v16, v134
	v_mul_f32_e32 v17, v17, v134
	v_mul_f32_e32 v18, v18, v134
	v_mul_f32_e32 v19, v19, v134
	v_fmac_f32_e32 v164, v28, v148
	v_fmac_f32_e32 v165, v29, v149
	v_fmac_f32_e32 v166, v30, v150
	v_fmac_f32_e32 v167, v31, v151
	v_fmac_f32_e32 v168, v16, v152
	v_fmac_f32_e32 v169, v17, v153
	v_fmac_f32_e32 v170, v18, v154
	v_fmac_f32_e32 v171, v19, v155
	v_mul_f32_e32 v145, v164, v164
	v_fmac_f32_e32 v145, v165, v165
	v_fmac_f32_e32 v145, v166, v166
	v_fmac_f32_e32 v145, v167, v167
	v_fmac_f32_e32 v145, v168, v168
	v_fmac_f32_e32 v145, v169, v169
	v_fmac_f32_e32 v145, v170, v170
	v_fmac_f32_e32 v145, v171, v171
	v_cvt_pk_bf16_f32 v180, v164, v165
	v_cvt_pk_bf16_f32 v181, v166, v167
	v_cvt_pk_bf16_f32 v182, v168, v169
	v_cvt_pk_bf16_f32 v183, v170, v171
	global_store_dwordx4 v140, v[180:183], s[22:23]
	v_lshlrev_b32_e32 v172, 16, v240
	v_and_b32_e32 v173, 0xffff0000, v240
	v_lshlrev_b32_e32 v174, 16, v241
	v_and_b32_e32 v175, 0xffff0000, v241
	v_lshlrev_b32_e32 v176, 16, v242
	v_and_b32_e32 v177, 0xffff0000, v242
	v_lshlrev_b32_e32 v178, 16, v243
	v_and_b32_e32 v179, 0xffff0000, v243
	v_mul_f32_e32 v20, v20, v134
	v_mul_f32_e32 v21, v21, v134
	v_mul_f32_e32 v22, v22, v134
	v_mul_f32_e32 v23, v23, v134
	v_mul_f32_e32 v24, v24, v134
	v_mul_f32_e32 v25, v25, v134
	v_mul_f32_e32 v26, v26, v134
	v_mul_f32_e32 v27, v27, v134
	v_fmac_f32_e32 v172, v20, v156
	v_fmac_f32_e32 v173, v21, v157
	v_fmac_f32_e32 v174, v22, v158
	v_fmac_f32_e32 v175, v23, v159
	v_fmac_f32_e32 v176, v24, v160
	v_fmac_f32_e32 v177, v25, v161
	v_fmac_f32_e32 v178, v26, v162
	v_fmac_f32_e32 v179, v27, v163
	v_fmac_f32_e32 v145, v172, v172
	v_fmac_f32_e32 v145, v173, v173
	v_fmac_f32_e32 v145, v174, v174
	v_fmac_f32_e32 v145, v175, v175
	v_fmac_f32_e32 v145, v176, v176
	v_fmac_f32_e32 v145, v177, v177
	v_fmac_f32_e32 v145, v178, v178
	v_fmac_f32_e32 v145, v179, v179
	v_cvt_pk_bf16_f32 v184, v172, v173
	v_cvt_pk_bf16_f32 v185, v174, v175
	v_cvt_pk_bf16_f32 v186, v176, v177
	v_cvt_pk_bf16_f32 v187, v178, v179
	global_store_dwordx4 v140, v[184:187], s[22:23] offset:256
	s_add_u32 s22, s64, 0x58000
	s_addc_u32 s23, s65, 0
	v_lshlrev_b32_e32 v164, 16, v244
	v_and_b32_e32 v165, 0xffff0000, v244
	v_lshlrev_b32_e32 v166, 16, v245
	v_and_b32_e32 v167, 0xffff0000, v245
	v_lshlrev_b32_e32 v168, 16, v246
	v_and_b32_e32 v169, 0xffff0000, v246
	v_lshlrev_b32_e32 v170, 16, v247
	v_and_b32_e32 v171, 0xffff0000, v247
	v_mul_f32_e32 v12, v12, v135
	v_mul_f32_e32 v13, v13, v135
	v_mul_f32_e32 v14, v14, v135
	v_mul_f32_e32 v15, v15, v135
	v_mul_f32_e32 v0, v0, v135
	v_mul_f32_e32 v1, v1, v135
	v_mul_f32_e32 v2, v2, v135
	v_mul_f32_e32 v3, v3, v135
	v_fmac_f32_e32 v164, v12, v148
	v_fmac_f32_e32 v165, v13, v149
	v_fmac_f32_e32 v166, v14, v150
	v_fmac_f32_e32 v167, v15, v151
	v_fmac_f32_e32 v168, v0, v152
	v_fmac_f32_e32 v169, v1, v153
	v_fmac_f32_e32 v170, v2, v154
	v_fmac_f32_e32 v171, v3, v155
	v_mul_f32_e32 v146, v164, v164
	v_fmac_f32_e32 v146, v165, v165
	v_fmac_f32_e32 v146, v166, v166
	v_fmac_f32_e32 v146, v167, v167
	v_fmac_f32_e32 v146, v168, v168
	v_fmac_f32_e32 v146, v169, v169
	v_fmac_f32_e32 v146, v170, v170
	v_fmac_f32_e32 v146, v171, v171
	v_cvt_pk_bf16_f32 v180, v164, v165
	v_cvt_pk_bf16_f32 v181, v166, v167
	v_cvt_pk_bf16_f32 v182, v168, v169
	v_cvt_pk_bf16_f32 v183, v170, v171
	global_store_dwordx4 v140, v[180:183], s[22:23]
	v_lshlrev_b32_e32 v172, 16, v248
	v_and_b32_e32 v173, 0xffff0000, v248
	v_lshlrev_b32_e32 v174, 16, v249
	v_and_b32_e32 v175, 0xffff0000, v249
	v_lshlrev_b32_e32 v176, 16, v250
	v_and_b32_e32 v177, 0xffff0000, v250
	v_lshlrev_b32_e32 v178, 16, v251
	v_and_b32_e32 v179, 0xffff0000, v251
	v_mul_f32_e32 v4, v4, v135
	v_mul_f32_e32 v5, v5, v135
	v_mul_f32_e32 v6, v6, v135
	v_mul_f32_e32 v7, v7, v135
	v_mul_f32_e32 v8, v8, v135
	v_mul_f32_e32 v9, v9, v135
	v_mul_f32_e32 v10, v10, v135
	v_mul_f32_e32 v11, v11, v135
	v_fmac_f32_e32 v172, v4, v156
	v_fmac_f32_e32 v173, v5, v157
	v_fmac_f32_e32 v174, v6, v158
	v_fmac_f32_e32 v175, v7, v159
	v_fmac_f32_e32 v176, v8, v160
	v_fmac_f32_e32 v177, v9, v161
	v_fmac_f32_e32 v178, v10, v162
	v_fmac_f32_e32 v179, v11, v163
	v_fmac_f32_e32 v146, v172, v172
	v_fmac_f32_e32 v146, v173, v173
	v_fmac_f32_e32 v146, v174, v174
	v_fmac_f32_e32 v146, v175, v175
	v_fmac_f32_e32 v146, v176, v176
	v_fmac_f32_e32 v146, v177, v177
	v_fmac_f32_e32 v146, v178, v178
	v_fmac_f32_e32 v146, v179, v179
	v_cvt_pk_bf16_f32 v184, v172, v173
	v_cvt_pk_bf16_f32 v185, v174, v175
	v_cvt_pk_bf16_f32 v186, v176, v177
	v_cvt_pk_bf16_f32 v187, v178, v179
	global_store_dwordx4 v140, v[184:187], s[22:23] offset:256
	v_mov_b32_e32 v148, v138
	v_mov_b32_e32 v149, v139
	v_mov_b32_e32 v150, v141
	v_mov_b32_e32 v151, v142
	v_mov_b32_e32 v152, v143
	v_mov_b32_e32 v153, v144
	v_mov_b32_e32 v154, v145
	v_mov_b32_e32 v155, v146
	v_xor_b32_e32 v138, 16, v137
	v_xor_b32_e32 v139, 32, v137
	v_lshlrev_b32_e32 v138, 2, v138
	v_lshlrev_b32_e32 v139, 2, v139
	ds_bpermute_b32 v164, v138, v148
	ds_bpermute_b32 v165, v138, v149
	ds_bpermute_b32 v166, v138, v150
	ds_bpermute_b32 v167, v138, v151
	ds_bpermute_b32 v168, v138, v152
	ds_bpermute_b32 v169, v138, v153
	ds_bpermute_b32 v170, v138, v154
	ds_bpermute_b32 v171, v138, v155
	s_waitcnt lgkmcnt(0)
	v_add_f32_e32 v148, v148, v164
	v_add_f32_e32 v149, v149, v165
	v_add_f32_e32 v150, v150, v166
	v_add_f32_e32 v151, v151, v167
	v_add_f32_e32 v152, v152, v168
	v_add_f32_e32 v153, v153, v169
	v_add_f32_e32 v154, v154, v170
	v_add_f32_e32 v155, v155, v171
	ds_bpermute_b32 v164, v139, v148
	ds_bpermute_b32 v165, v139, v149
	ds_bpermute_b32 v166, v139, v150
	ds_bpermute_b32 v167, v139, v151
	ds_bpermute_b32 v168, v139, v152
	ds_bpermute_b32 v169, v139, v153
	ds_bpermute_b32 v170, v139, v154
	ds_bpermute_b32 v171, v139, v155
	s_waitcnt lgkmcnt(0)
	v_add_f32_e32 v148, v148, v164
	v_add_f32_e32 v149, v149, v165
	v_add_f32_e32 v150, v150, v166
	v_add_f32_e32 v151, v151, v167
	v_add_f32_e32 v152, v152, v168
	v_add_f32_e32 v153, v153, v169
	v_add_f32_e32 v154, v154, v170
	v_add_f32_e32 v155, v155, v171
	s_and_b32 s98, s2, 7
	s_lshl_b32 s98, s98, 3
	s_bfe_u32 s99, s2, 0x30003
	s_or_b32 s98, s98, s99
	s_lshr_b32 s99, s2, 6
	s_mul_i32 s99, s99, 0x42000
	s_lshl_b32 s98, s98, 10
	s_add_u32 s100, s62, s99
	s_addc_u32 s101, s63, 0
	s_add_u32 s100, s100, s98
	s_addc_u32 s101, s101, 0
	v_lshrrev_b32_e32 v158, 8, v136
	v_bfe_u32 v159, v136, 6, 2
	v_and_b32_e32 v160, 15, v136
	v_lshl_add_u32 v160, v158, 6, v160
	v_mul_u32_u24_e32 v159, 0x4200, v159
	v_add_u32_e32 v160, v160, v159
	v_lshlrev_b32_e32 v160, 2, v160
	v_bfe_u32 v161, v136, 4, 2
	v_cmp_eq_u32_e32 vcc, 0, v161
	s_and_saveexec_b64 s[0:1], vcc
	global_store_dword v160, v148, s[100:101]
	global_store_dword v160, v149, s[100:101] offset:64
	global_store_dword v160, v150, s[100:101] offset:128
	global_store_dword v160, v151, s[100:101] offset:192
	global_store_dword v160, v152, s[100:101] offset:512
	global_store_dword v160, v153, s[100:101] offset:576
	global_store_dword v160, v154, s[100:101] offset:640
	global_store_dword v160, v155, s[100:101] offset:704
	s_or_b64 exec, exec, s[0:1]
	v_bfe_u32 v183, v136, 1, 2
	v_lshrrev_b32_e32 v187, 6, v136
	v_lshlrev_b32_e32 v190, 11, v136
	v_lshrrev_b32_e32 v252, 1, v136
	v_and_b32_e32 v132, 48, v136
	v_and_b32_e32 v189, 63, v136
	v_lshrrev_b32_e32 v182, 3, v136
	v_lshlrev_b32_e32 v188, 2, v136
	v_lshl_add_u32 v186, v183, 6, 0
	v_and_b32_e32 v191, 15, v136
	v_cndmask_b32_e64 v1, 0, 1, s[8:9]
	v_mov_b32_e32 v0, v136
	v_cmp_ne_u32_e64 s[6:7], 1, v1
	s_andn2_b64 vcc, exec, s[8:9]
	s_cbranch_vccnz .LBB0_1254
	v_and_b32_e32 v4, 63, v0
	v_ashrrev_i32_e32 v0, 5, v0
	v_readlane_b32 s8, v253, 3
	v_and_b32_e32 v5, -2, v0
	v_lshlrev_b32_e32 v0, 4, v4
	v_mov_b32_e32 v1, 0
	v_readlane_b32 s9, v253, 4
	s_mov_b64 s[0:1], 0x3000
	v_readlane_b32 s12, v253, 7
	v_lshl_add_u64 v[2:3], s[8:9], 0, v[0:1]
	v_lshl_add_u64 v[16:17], v[2:3], 0, s[0:1]
	v_and_b32_e32 v2, 64, v137
	v_add_u32_e32 v2, 64, v2
	v_xor_b32_e32 v3, 32, v137
	v_cmp_lt_i32_e64 s[0:1], v3, v2
	v_mul_u32_u24_e32 v0, 0x4200, v4
	v_lshlrev_b32_e32 v0, 2, v0
	v_cndmask_b32_e64 v3, v137, v3, s[0:1]
	v_lshlrev_b32_e32 v50, 2, v3
	v_xor_b32_e32 v3, 16, v137
	v_cmp_lt_i32_e64 s[0:1], v3, v2
	v_readlane_b32 s13, v253, 8
	v_lshl_add_u64 v[18:19], s[44:45], 0, v[0:1]
	v_cndmask_b32_e64 v3, v137, v3, s[0:1]
	v_lshlrev_b32_e32 v51, 2, v3
	v_xor_b32_e32 v3, 8, v137
	v_cmp_lt_i32_e64 s[0:1], v3, v2
	v_lshlrev_b32_e32 v0, 3, v4
	v_cmp_gt_u32_e32 vcc, 16, v4
	v_cndmask_b32_e64 v3, v137, v3, s[0:1]
	v_lshlrev_b32_e32 v52, 2, v3
	v_xor_b32_e32 v3, 4, v137
	v_cmp_lt_i32_e64 s[0:1], v3, v2
	v_lshl_add_u64 v[20:21], s[64:65], 0, v[0:1]
	v_lshl_add_u64 v[22:23], s[60:61], 0, v[0:1]
	v_cndmask_b32_e64 v3, v137, v3, s[0:1]
	v_lshlrev_b32_e32 v53, 2, v3
	v_xor_b32_e32 v3, 2, v137
	v_cmp_lt_i32_e64 s[0:1], v3, v2
	v_lshl_add_u64 v[24:25], s[58:59], 0, v[0:1]
	v_lshl_add_u32 v26, s2, 4, v5
	v_cndmask_b32_e64 v3, v137, v3, s[0:1]
	v_lshlrev_b32_e32 v54, 2, v3
	v_xor_b32_e32 v3, 1, v137
	v_cmp_lt_i32_e64 s[0:1], v3, v2
	s_lshl_b32 s3, s38, 4
	v_mov_b32_e32 v56, 0x358637bd
	v_cndmask_b32_e64 v2, v137, v3, s[0:1]
	v_lshlrev_b32_e32 v55, 2, v2
	v_cmp_eq_u32_e64 s[0:1], 0, v4
	s_mov_b32 s12, 0x800000
	s_mov_b32 s13, s2
	v_readlane_b32 s10, v253, 5
	v_readlane_b32 s11, v253, 6
	v_readlane_b32 s14, v253, 9
	v_readlane_b32 s15, v253, 10
	v_readlane_b32 s16, v253, 11
	v_readlane_b32 s17, v253, 12
	v_readlane_b32 s18, v253, 13
	v_readlane_b32 s19, v253, 14
	v_readlane_b32 s20, v253, 15
	v_readlane_b32 s21, v253, 16
	v_readlane_b32 s22, v253, 17
	v_readlane_b32 s23, v253, 18
	s_addk_i32 s13, 0x400
	v_add_u32_e32 v26, 0x4000, v26
	s_cmpk_lt_i32 s13, 0x420
	s_cbranch_scc0 .LBB0_1254
	s_branch .LBB0_1246

.LBB0_1468:
	s_or_b64 exec, exec, s[0:1]
	s_and_b64 vcc, exec, s[6:7]
	s_waitcnt lgkmcnt(0)
	s_barrier
	s_and_b32 s99, s2, 7
	s_lshl_b32 s99, s99, 3
	s_bfe_u32 s100, s2, 0x30003
	s_or_b32 s99, s99, s100
	s_lshr_b32 s100, s2, 6
	v_and_b32_e32 v172, 0xff, v136
	v_lshrrev_b32_e32 v173, 8, v136
	v_mul_u32_u24_e32 v173, 0x84000, v173
	v_lshl_add_u32 v172, v172, 2, v173
	s_lshl_b32 s24, s99, 10
	s_add_u32 s18, s44, s24
	s_addc_u32 s19, s45, 0
	global_load_dword v164, v172, s[18:19]
	s_add_u32 s18, s18, 0x10800
	s_addc_u32 s19, s19, 0
	global_load_dword v165, v172, s[18:19]
	s_add_u32 s18, s18, 0x10800
	s_addc_u32 s19, s19, 0
	global_load_dword v166, v172, s[18:19]
	s_add_u32 s18, s18, 0x10800
	s_addc_u32 s19, s19, 0
	global_load_dword v167, v172, s[18:19]
	s_add_u32 s18, s18, 0x10800
	s_addc_u32 s19, s19, 0
	global_load_dword v168, v172, s[18:19]
	s_add_u32 s18, s18, 0x10800
	s_addc_u32 s19, s19, 0
	global_load_dword v169, v172, s[18:19]
	s_add_u32 s18, s18, 0x10800
	s_addc_u32 s19, s19, 0
	global_load_dword v170, v172, s[18:19]
	s_add_u32 s18, s18, 0x10800
	s_addc_u32 s19, s19, 0
	global_load_dword v171, v172, s[18:19]
	v_lshrrev_b32_e32 v141, 8, v136
	v_and_b32_e32 v142, 15, v136
	v_lshl_add_u32 v141, v141, 6, v142
	v_bfe_u32 v144, v136, 6, 2
	v_bfe_u32 v145, v136, 4, 2
	v_lshlrev_b32_e32 v144, 5, v144
	v_lshl_add_u32 v144, v145, 3, v144
	s_lshl_b32 s24, s100, 8
	v_add_u32_e32 v144, s24, v144
	s_lshl_b32 s25, s99, 8
	v_add_u32_e32 v145, s25, v141
	v_lshl_add_u32 v146, v145, 10, v144
	v_lshlrev_b32_e32 v139, 1, v146
	v_lshlrev_b32_e32 v140, 2, v146
	v_lshlrev_b32_e32 v138, 2, v144
	v_readlane_b32 s18, v253, 3
	v_readlane_b32 s19, v253, 4
	v_readlane_b32 s20, v254, 52
	v_readlane_b32 s21, v254, 53
	s_nop 4
	s_add_u32 s18, s18, 0x5000
	s_addc_u32 s19, s19, 0
	global_load_dwordx4 v[148:151], v138, s[18:19]
	global_load_dwordx4 v[152:155], v138, s[18:19] offset:16
	global_load_dwordx4 v[156:159], v138, s[18:19] offset:512
	global_load_dwordx4 v[160:163], v138, s[18:19] offset:528
	s_add_u32 s22, s64, 0x0
	s_addc_u32 s23, s65, 0
	global_load_dwordx4 v[188:191], v139, s[22:23] nt
	global_load_dwordx4 v[192:195], v139, s[22:23] offset:256 nt
	s_add_u32 s22, s64, 0x8000
	s_addc_u32 s23, s65, 0
	global_load_dwordx4 v[196:199], v139, s[22:23] nt
	global_load_dwordx4 v[200:203], v139, s[22:23] offset:256 nt
	s_add_u32 s22, s64, 0x10000
	s_addc_u32 s23, s65, 0
	global_load_dwordx4 v[204:207], v139, s[22:23] nt
	global_load_dwordx4 v[208:211], v139, s[22:23] offset:256 nt
	s_add_u32 s22, s64, 0x18000
	s_addc_u32 s23, s65, 0
	global_load_dwordx4 v[212:215], v139, s[22:23] nt
	global_load_dwordx4 v[216:219], v139, s[22:23] offset:256 nt
	s_add_u32 s22, s64, 0x40000
	s_addc_u32 s23, s65, 0
	global_load_dwordx4 v[220:223], v139, s[22:23] nt
	global_load_dwordx4 v[224:227], v139, s[22:23] offset:256 nt
	s_add_u32 s22, s64, 0x48000
	s_addc_u32 s23, s65, 0
	global_load_dwordx4 v[228:231], v139, s[22:23] nt
	global_load_dwordx4 v[232:235], v139, s[22:23] offset:256 nt
	s_add_u32 s22, s64, 0x50000
	s_addc_u32 s23, s65, 0
	global_load_dwordx4 v[236:239], v139, s[22:23] nt
	global_load_dwordx4 v[240:243], v139, s[22:23] offset:256 nt
	s_add_u32 s22, s64, 0x58000
	s_addc_u32 s23, s65, 0
	global_load_dwordx4 v[244:247], v139, s[22:23] nt
	global_load_dwordx4 v[248:251], v139, s[22:23] offset:256 nt
	s_cmp_lt_u32 s2, 32
	s_cbranch_scc0 .Ltouch_2
	v_and_b32_e32 v185, 63, v136
	v_lshrrev_b32_e32 v186, 6, v136
	s_lshl_b32 s24, s2, 4
	s_add_i32 s24, s24, 0x4000
	v_lshl_add_u32 v186, v186, 1, s24
	v_lshlrev_b32_e32 v187, 11, v186
	v_lshl_add_u32 v187, v185, 6, v187
	global_load_dword v184, v187, s[64:65]
	global_load_dword v184, v187, s[58:59]
	v_and_b32_e32 v185, 15, v185
	v_mul_u32_u24_e32 v185, 0x10800, v185
	v_lshl_add_u32 v185, v186, 2, v185
	global_load_dword v184, v185, s[44:45]
.Ltouch_2:
	s_waitcnt vmcnt(20)
	v_add_f32_e32 v164, v164, v165
	v_add_f32_e32 v164, v164, v166
	v_add_f32_e32 v164, v164, v167
	v_add_f32_e32 v164, v164, v168
	v_add_f32_e32 v164, v164, v169
	v_add_f32_e32 v164, v164, v170
	v_add_f32_e32 v164, v164, v171
	v_lshlrev_b32_e32 v173, 2, v136
	ds_write_b32 v173, v164
	s_waitcnt lgkmcnt(0)
	s_barrier
	v_lshlrev_b32_e32 v142, 2, v141
	ds_read_b32 v128, v142 offset:0
	ds_read_b32 v174, v142 offset:1024
	ds_read_b32 v129, v142 offset:64
	ds_read_b32 v175, v142 offset:1088
	ds_read_b32 v130, v142 offset:128
	ds_read_b32 v176, v142 offset:1152
	ds_read_b32 v131, v142 offset:192
	ds_read_b32 v177, v142 offset:1216
	ds_read_b32 v132, v142 offset:512
	ds_read_b32 v178, v142 offset:1536
	ds_read_b32 v133, v142 offset:576
	ds_read_b32 v179, v142 offset:1600
	ds_read_b32 v134, v142 offset:640
	ds_read_b32 v180, v142 offset:1664
	ds_read_b32 v135, v142 offset:704
	ds_read_b32 v181, v142 offset:1728
	s_waitcnt lgkmcnt(0)
	s_mov_b32 s101, 0x3a800000
	v_mov_b32_e32 v143, 0x358637bd
	v_add_f32_e32 v128, v128, v174
	v_add_f32_e32 v129, v129, v175
	v_add_f32_e32 v130, v130, v176
	v_add_f32_e32 v131, v131, v177
	v_add_f32_e32 v132, v132, v178
	v_add_f32_e32 v133, v133, v179
	v_add_f32_e32 v134, v134, v180
	v_add_f32_e32 v135, v135, v181
	v_fma_f32 v128, v128, s101, v143
	v_fma_f32 v129, v129, s101, v143
	v_fma_f32 v130, v130, s101, v143
	v_fma_f32 v131, v131, s101, v143
	v_fma_f32 v132, v132, s101, v143
	v_fma_f32 v133, v133, s101, v143
	v_fma_f32 v134, v134, s101, v143
	v_fma_f32 v135, v135, s101, v143
	v_rsq_f32_e32 v128, v128
	v_rsq_f32_e32 v129, v129
	v_rsq_f32_e32 v130, v130
	v_rsq_f32_e32 v131, v131
	v_rsq_f32_e32 v132, v132
	v_rsq_f32_e32 v133, v133
	v_rsq_f32_e32 v134, v134
	v_rsq_f32_e32 v135, v135
	s_waitcnt vmcnt(0)
	s_add_u32 s22, s20, 0x0
	s_addc_u32 s23, s21, 0
	v_lshlrev_b32_e32 v164, 16, v188
	v_and_b32_e32 v165, 0xffff0000, v188
	v_lshlrev_b32_e32 v166, 16, v189
	v_and_b32_e32 v167, 0xffff0000, v189
	v_lshlrev_b32_e32 v168, 16, v190
	v_and_b32_e32 v169, 0xffff0000, v190
	v_lshlrev_b32_e32 v170, 16, v191
	v_and_b32_e32 v171, 0xffff0000, v191
	v_mul_f32_e32 v124, v124, v128
	v_mul_f32_e32 v125, v125, v128
	v_mul_f32_e32 v126, v126, v128
	v_mul_f32_e32 v127, v127, v128
	v_mul_f32_e32 v112, v112, v128
	v_mul_f32_e32 v113, v113, v128
	v_mul_f32_e32 v114, v114, v128
	v_mul_f32_e32 v115, v115, v128
	v_fmac_f32_e32 v164, v124, v148
	v_fmac_f32_e32 v165, v125, v149
	v_fmac_f32_e32 v166, v126, v150
	v_fmac_f32_e32 v167, v127, v151
	v_fmac_f32_e32 v168, v112, v152
	v_fmac_f32_e32 v169, v113, v153
	v_fmac_f32_e32 v170, v114, v154
	v_fmac_f32_e32 v171, v115, v155
	global_store_dwordx4 v140, v[164:167], s[22:23]
	global_store_dwordx4 v140, v[168:171], s[22:23] offset:16
	v_lshlrev_b32_e32 v172, 16, v192
	v_and_b32_e32 v173, 0xffff0000, v192
	v_lshlrev_b32_e32 v174, 16, v193
	v_and_b32_e32 v175, 0xffff0000, v193
	v_lshlrev_b32_e32 v176, 16, v194
	v_and_b32_e32 v177, 0xffff0000, v194
	v_lshlrev_b32_e32 v178, 16, v195
	v_and_b32_e32 v179, 0xffff0000, v195
	v_mul_f32_e32 v120, v120, v128
	v_mul_f32_e32 v121, v121, v128
	v_mul_f32_e32 v122, v122, v128
	v_mul_f32_e32 v123, v123, v128
	v_mul_f32_e32 v116, v116, v128
	v_mul_f32_e32 v117, v117, v128
	v_mul_f32_e32 v118, v118, v128
	v_mul_f32_e32 v119, v119, v128
	v_fmac_f32_e32 v172, v120, v156
	v_fmac_f32_e32 v173, v121, v157
	v_fmac_f32_e32 v174, v122, v158
	v_fmac_f32_e32 v175, v123, v159
	v_fmac_f32_e32 v176, v116, v160
	v_fmac_f32_e32 v177, v117, v161
	v_fmac_f32_e32 v178, v118, v162
	v_fmac_f32_e32 v179, v119, v163
	global_store_dwordx4 v140, v[172:175], s[22:23] offset:512
	global_store_dwordx4 v140, v[176:179], s[22:23] offset:528
	s_add_u32 s22, s20, 0x10000
	s_addc_u32 s23, s21, 0
	v_lshlrev_b32_e32 v180, 16, v196
	v_and_b32_e32 v181, 0xffff0000, v196
	v_lshlrev_b32_e32 v182, 16, v197
	v_and_b32_e32 v183, 0xffff0000, v197
	v_lshlrev_b32_e32 v184, 16, v198
	v_and_b32_e32 v185, 0xffff0000, v198
	v_lshlrev_b32_e32 v186, 16, v199
	v_and_b32_e32 v187, 0xffff0000, v199
	v_mul_f32_e32 v108, v108, v129
	v_mul_f32_e32 v109, v109, v129
	v_mul_f32_e32 v110, v110, v129
	v_mul_f32_e32 v111, v111, v129
	v_mul_f32_e32 v96, v96, v129
	v_mul_f32_e32 v97, v97, v129
	v_mul_f32_e32 v98, v98, v129
	v_mul_f32_e32 v99, v99, v129
	v_fmac_f32_e32 v180, v108, v148
	v_fmac_f32_e32 v181, v109, v149
	v_fmac_f32_e32 v182, v110, v150
	v_fmac_f32_e32 v183, v111, v151
	v_fmac_f32_e32 v184, v96, v152
	v_fmac_f32_e32 v185, v97, v153
	v_fmac_f32_e32 v186, v98, v154
	v_fmac_f32_e32 v187, v99, v155
	global_store_dwordx4 v140, v[180:183], s[22:23]
	global_store_dwordx4 v140, v[184:187], s[22:23] offset:16
	v_lshlrev_b32_e32 v164, 16, v200
	v_and_b32_e32 v165, 0xffff0000, v200
	v_lshlrev_b32_e32 v166, 16, v201
	v_and_b32_e32 v167, 0xffff0000, v201
	v_lshlrev_b32_e32 v168, 16, v202
	v_and_b32_e32 v169, 0xffff0000, v202
	v_lshlrev_b32_e32 v170, 16, v203
	v_and_b32_e32 v171, 0xffff0000, v203
	v_mul_f32_e32 v100, v100, v129
	v_mul_f32_e32 v101, v101, v129
	v_mul_f32_e32 v102, v102, v129
	v_mul_f32_e32 v103, v103, v129
	v_mul_f32_e32 v104, v104, v129
	v_mul_f32_e32 v105, v105, v129
	v_mul_f32_e32 v106, v106, v129
	v_mul_f32_e32 v107, v107, v129
	v_fmac_f32_e32 v164, v100, v156
	v_fmac_f32_e32 v165, v101, v157
	v_fmac_f32_e32 v166, v102, v158
	v_fmac_f32_e32 v167, v103, v159
	v_fmac_f32_e32 v168, v104, v160
	v_fmac_f32_e32 v169, v105, v161
	v_fmac_f32_e32 v170, v106, v162
	v_fmac_f32_e32 v171, v107, v163
	global_store_dwordx4 v140, v[164:167], s[22:23] offset:512
	global_store_dwordx4 v140, v[168:171], s[22:23] offset:528
	s_add_u32 s22, s20, 0x20000
	s_addc_u32 s23, s21, 0
	v_lshlrev_b32_e32 v172, 16, v204
	v_and_b32_e32 v173, 0xffff0000, v204
	v_lshlrev_b32_e32 v174, 16, v205
	v_and_b32_e32 v175, 0xffff0000, v205
	v_lshlrev_b32_e32 v176, 16, v206
	v_and_b32_e32 v177, 0xffff0000, v206
	v_lshlrev_b32_e32 v178, 16, v207
	v_and_b32_e32 v179, 0xffff0000, v207
	v_mul_f32_e32 v92, v92, v130
	v_mul_f32_e32 v93, v93, v130
	v_mul_f32_e32 v94, v94, v130
	v_mul_f32_e32 v95, v95, v130
	v_mul_f32_e32 v80, v80, v130
	v_mul_f32_e32 v81, v81, v130
	v_mul_f32_e32 v82, v82, v130
	v_mul_f32_e32 v83, v83, v130
	v_fmac_f32_e32 v172, v92, v148
	v_fmac_f32_e32 v173, v93, v149
	v_fmac_f32_e32 v174, v94, v150
	v_fmac_f32_e32 v175, v95, v151
	v_fmac_f32_e32 v176, v80, v152
	v_fmac_f32_e32 v177, v81, v153
	v_fmac_f32_e32 v178, v82, v154
	v_fmac_f32_e32 v179, v83, v155
	global_store_dwordx4 v140, v[172:175], s[22:23]
	global_store_dwordx4 v140, v[176:179], s[22:23] offset:16
	v_lshlrev_b32_e32 v180, 16, v208
	v_and_b32_e32 v181, 0xffff0000, v208
	v_lshlrev_b32_e32 v182, 16, v209
	v_and_b32_e32 v183, 0xffff0000, v209
	v_lshlrev_b32_e32 v184, 16, v210
	v_and_b32_e32 v185, 0xffff0000, v210
	v_lshlrev_b32_e32 v186, 16, v211
	v_and_b32_e32 v187, 0xffff0000, v211
	v_mul_f32_e32 v84, v84, v130
	v_mul_f32_e32 v85, v85, v130
	v_mul_f32_e32 v86, v86, v130
	v_mul_f32_e32 v87, v87, v130
	v_mul_f32_e32 v88, v88, v130
	v_mul_f32_e32 v89, v89, v130
	v_mul_f32_e32 v90, v90, v130
	v_mul_f32_e32 v91, v91, v130
	v_fmac_f32_e32 v180, v84, v156
	v_fmac_f32_e32 v181, v85, v157
	v_fmac_f32_e32 v182, v86, v158
	v_fmac_f32_e32 v183, v87, v159
	v_fmac_f32_e32 v184, v88, v160
	v_fmac_f32_e32 v185, v89, v161
	v_fmac_f32_e32 v186, v90, v162
	v_fmac_f32_e32 v187, v91, v163
	global_store_dwordx4 v140, v[180:183], s[22:23] offset:512
	global_store_dwordx4 v140, v[184:187], s[22:23] offset:528
	s_add_u32 s22, s20, 0x30000
	s_addc_u32 s23, s21, 0
	v_lshlrev_b32_e32 v164, 16, v212
	v_and_b32_e32 v165, 0xffff0000, v212
	v_lshlrev_b32_e32 v166, 16, v213
	v_and_b32_e32 v167, 0xffff0000, v213
	v_lshlrev_b32_e32 v168, 16, v214
	v_and_b32_e32 v169, 0xffff0000, v214
	v_lshlrev_b32_e32 v170, 16, v215
	v_and_b32_e32 v171, 0xffff0000, v215
	v_mul_f32_e32 v76, v76, v131
	v_mul_f32_e32 v77, v77, v131
	v_mul_f32_e32 v78, v78, v131
	v_mul_f32_e32 v79, v79, v131
	v_mul_f32_e32 v64, v64, v131
	v_mul_f32_e32 v65, v65, v131
	v_mul_f32_e32 v66, v66, v131
	v_mul_f32_e32 v67, v67, v131
	v_fmac_f32_e32 v164, v76, v148
	v_fmac_f32_e32 v165, v77, v149
	v_fmac_f32_e32 v166, v78, v150
	v_fmac_f32_e32 v167, v79, v151
	v_fmac_f32_e32 v168, v64, v152
	v_fmac_f32_e32 v169, v65, v153
	v_fmac_f32_e32 v170, v66, v154
	v_fmac_f32_e32 v171, v67, v155
	global_store_dwordx4 v140, v[164:167], s[22:23]
	global_store_dwordx4 v140, v[168:171], s[22:23] offset:16
	v_lshlrev_b32_e32 v172, 16, v216
	v_and_b32_e32 v173, 0xffff0000, v216
	v_lshlrev_b32_e32 v174, 16, v217
	v_and_b32_e32 v175, 0xffff0000, v217
	v_lshlrev_b32_e32 v176, 16, v218
	v_and_b32_e32 v177, 0xffff0000, v218
	v_lshlrev_b32_e32 v178, 16, v219
	v_and_b32_e32 v179, 0xffff0000, v219
	v_mul_f32_e32 v68, v68, v131
	v_mul_f32_e32 v69, v69, v131
	v_mul_f32_e32 v70, v70, v131
	v_mul_f32_e32 v71, v71, v131
	v_mul_f32_e32 v72, v72, v131
	v_mul_f32_e32 v73, v73, v131
	v_mul_f32_e32 v74, v74, v131
	v_mul_f32_e32 v75, v75, v131
	v_fmac_f32_e32 v172, v68, v156
	v_fmac_f32_e32 v173, v69, v157
	v_fmac_f32_e32 v174, v70, v158
	v_fmac_f32_e32 v175, v71, v159
	v_fmac_f32_e32 v176, v72, v160
	v_fmac_f32_e32 v177, v73, v161
	v_fmac_f32_e32 v178, v74, v162
	v_fmac_f32_e32 v179, v75, v163
	global_store_dwordx4 v140, v[172:175], s[22:23] offset:512
	global_store_dwordx4 v140, v[176:179], s[22:23] offset:528
	s_add_u32 s22, s20, 0x80000
	s_addc_u32 s23, s21, 0
	v_lshlrev_b32_e32 v180, 16, v220
	v_and_b32_e32 v181, 0xffff0000, v220
	v_lshlrev_b32_e32 v182, 16, v221
	v_and_b32_e32 v183, 0xffff0000, v221
	v_lshlrev_b32_e32 v184, 16, v222
	v_and_b32_e32 v185, 0xffff0000, v222
	v_lshlrev_b32_e32 v186, 16, v223
	v_and_b32_e32 v187, 0xffff0000, v223
	v_mul_f32_e32 v60, v60, v132
	v_mul_f32_e32 v61, v61, v132
	v_mul_f32_e32 v62, v62, v132
	v_mul_f32_e32 v63, v63, v132
	v_mul_f32_e32 v48, v48, v132
	v_mul_f32_e32 v49, v49, v132
	v_mul_f32_e32 v50, v50, v132
	v_mul_f32_e32 v51, v51, v132
	v_fmac_f32_e32 v180, v60, v148
	v_fmac_f32_e32 v181, v61, v149
	v_fmac_f32_e32 v182, v62, v150
	v_fmac_f32_e32 v183, v63, v151
	v_fmac_f32_e32 v184, v48, v152
	v_fmac_f32_e32 v185, v49, v153
	v_fmac_f32_e32 v186, v50, v154
	v_fmac_f32_e32 v187, v51, v155
	global_store_dwordx4 v140, v[180:183], s[22:23]
	global_store_dwordx4 v140, v[184:187], s[22:23] offset:16
	v_lshlrev_b32_e32 v164, 16, v224
	v_and_b32_e32 v165, 0xffff0000, v224
	v_lshlrev_b32_e32 v166, 16, v225
	v_and_b32_e32 v167, 0xffff0000, v225
	v_lshlrev_b32_e32 v168, 16, v226
	v_and_b32_e32 v169, 0xffff0000, v226
	v_lshlrev_b32_e32 v170, 16, v227
	v_and_b32_e32 v171, 0xffff0000, v227
	v_mul_f32_e32 v52, v52, v132
	v_mul_f32_e32 v53, v53, v132
	v_mul_f32_e32 v54, v54, v132
	v_mul_f32_e32 v55, v55, v132
	v_mul_f32_e32 v56, v56, v132
	v_mul_f32_e32 v57, v57, v132
	v_mul_f32_e32 v58, v58, v132
	v_mul_f32_e32 v59, v59, v132
	v_fmac_f32_e32 v164, v52, v156
	v_fmac_f32_e32 v165, v53, v157
	v_fmac_f32_e32 v166, v54, v158
	v_fmac_f32_e32 v167, v55, v159
	v_fmac_f32_e32 v168, v56, v160
	v_fmac_f32_e32 v169, v57, v161
	v_fmac_f32_e32 v170, v58, v162
	v_fmac_f32_e32 v171, v59, v163
	global_store_dwordx4 v140, v[164:167], s[22:23] offset:512
	global_store_dwordx4 v140, v[168:171], s[22:23] offset:528
	s_add_u32 s22, s20, 0x90000
	s_addc_u32 s23, s21, 0
	v_lshlrev_b32_e32 v172, 16, v228
	v_and_b32_e32 v173, 0xffff0000, v228
	v_lshlrev_b32_e32 v174, 16, v229
	v_and_b32_e32 v175, 0xffff0000, v229
	v_lshlrev_b32_e32 v176, 16, v230
	v_and_b32_e32 v177, 0xffff0000, v230
	v_lshlrev_b32_e32 v178, 16, v231
	v_and_b32_e32 v179, 0xffff0000, v231
	v_mul_f32_e32 v44, v44, v133
	v_mul_f32_e32 v45, v45, v133
	v_mul_f32_e32 v46, v46, v133
	v_mul_f32_e32 v47, v47, v133
	v_mul_f32_e32 v32, v32, v133
	v_mul_f32_e32 v33, v33, v133
	v_mul_f32_e32 v34, v34, v133
	v_mul_f32_e32 v35, v35, v133
	v_fmac_f32_e32 v172, v44, v148
	v_fmac_f32_e32 v173, v45, v149
	v_fmac_f32_e32 v174, v46, v150
	v_fmac_f32_e32 v175, v47, v151
	v_fmac_f32_e32 v176, v32, v152
	v_fmac_f32_e32 v177, v33, v153
	v_fmac_f32_e32 v178, v34, v154
	v_fmac_f32_e32 v179, v35, v155
	global_store_dwordx4 v140, v[172:175], s[22:23]
	global_store_dwordx4 v140, v[176:179], s[22:23] offset:16
	v_lshlrev_b32_e32 v180, 16, v232
	v_and_b32_e32 v181, 0xffff0000, v232
	v_lshlrev_b32_e32 v182, 16, v233
	v_and_b32_e32 v183, 0xffff0000, v233
	v_lshlrev_b32_e32 v184, 16, v234
	v_and_b32_e32 v185, 0xffff0000, v234
	v_lshlrev_b32_e32 v186, 16, v235
	v_and_b32_e32 v187, 0xffff0000, v235
	v_mul_f32_e32 v36, v36, v133
	v_mul_f32_e32 v37, v37, v133
	v_mul_f32_e32 v38, v38, v133
	v_mul_f32_e32 v39, v39, v133
	v_mul_f32_e32 v40, v40, v133
	v_mul_f32_e32 v41, v41, v133
	v_mul_f32_e32 v42, v42, v133
	v_mul_f32_e32 v43, v43, v133
	v_fmac_f32_e32 v180, v36, v156
	v_fmac_f32_e32 v181, v37, v157
	v_fmac_f32_e32 v182, v38, v158
	v_fmac_f32_e32 v183, v39, v159
	v_fmac_f32_e32 v184, v40, v160
	v_fmac_f32_e32 v185, v41, v161
	v_fmac_f32_e32 v186, v42, v162
	v_fmac_f32_e32 v187, v43, v163
	global_store_dwordx4 v140, v[180:183], s[22:23] offset:512
	global_store_dwordx4 v140, v[184:187], s[22:23] offset:528
	s_add_u32 s22, s20, 0xa0000
	s_addc_u32 s23, s21, 0
	v_lshlrev_b32_e32 v164, 16, v236
	v_and_b32_e32 v165, 0xffff0000, v236
	v_lshlrev_b32_e32 v166, 16, v237
	v_and_b32_e32 v167, 0xffff0000, v237
	v_lshlrev_b32_e32 v168, 16, v238
	v_and_b32_e32 v169, 0xffff0000, v238
	v_lshlrev_b32_e32 v170, 16, v239
	v_and_b32_e32 v171, 0xffff0000, v239
	v_mul_f32_e32 v28, v28, v134
	v_mul_f32_e32 v29, v29, v134
	v_mul_f32_e32 v30, v30, v134
	v_mul_f32_e32 v31, v31, v134
	v_mul_f32_e32 v16, v16, v134
	v_mul_f32_e32 v17, v17, v134
	v_mul_f32_e32 v18, v18, v134
	v_mul_f32_e32 v19, v19, v134
	v_fmac_f32_e32 v164, v28, v148
	v_fmac_f32_e32 v165, v29, v149
	v_fmac_f32_e32 v166, v30, v150
	v_fmac_f32_e32 v167, v31, v151
	v_fmac_f32_e32 v168, v16, v152
	v_fmac_f32_e32 v169, v17, v153
	v_fmac_f32_e32 v170, v18, v154
	v_fmac_f32_e32 v171, v19, v155
	global_store_dwordx4 v140, v[164:167], s[22:23]
	global_store_dwordx4 v140, v[168:171], s[22:23] offset:16
	v_lshlrev_b32_e32 v172, 16, v240
	v_and_b32_e32 v173, 0xffff0000, v240
	v_lshlrev_b32_e32 v174, 16, v241
	v_and_b32_e32 v175, 0xffff0000, v241
	v_lshlrev_b32_e32 v176, 16, v242
	v_and_b32_e32 v177, 0xffff0000, v242
	v_lshlrev_b32_e32 v178, 16, v243
	v_and_b32_e32 v179, 0xffff0000, v243
	v_mul_f32_e32 v20, v20, v134
	v_mul_f32_e32 v21, v21, v134
	v_mul_f32_e32 v22, v22, v134
	v_mul_f32_e32 v23, v23, v134
	v_mul_f32_e32 v24, v24, v134
	v_mul_f32_e32 v25, v25, v134
	v_mul_f32_e32 v26, v26, v134
	v_mul_f32_e32 v27, v27, v134
	v_fmac_f32_e32 v172, v20, v156
	v_fmac_f32_e32 v173, v21, v157
	v_fmac_f32_e32 v174, v22, v158
	v_fmac_f32_e32 v175, v23, v159
	v_fmac_f32_e32 v176, v24, v160
	v_fmac_f32_e32 v177, v25, v161
	v_fmac_f32_e32 v178, v26, v162
	v_fmac_f32_e32 v179, v27, v163
	global_store_dwordx4 v140, v[172:175], s[22:23] offset:512
	global_store_dwordx4 v140, v[176:179], s[22:23] offset:528
	s_add_u32 s22, s20, 0xb0000
	s_addc_u32 s23, s21, 0
	v_lshlrev_b32_e32 v180, 16, v244
	v_and_b32_e32 v181, 0xffff0000, v244
	v_lshlrev_b32_e32 v182, 16, v245
	v_and_b32_e32 v183, 0xffff0000, v245
	v_lshlrev_b32_e32 v184, 16, v246
	v_and_b32_e32 v185, 0xffff0000, v246
	v_lshlrev_b32_e32 v186, 16, v247
	v_and_b32_e32 v187, 0xffff0000, v247
	v_mul_f32_e32 v12, v12, v135
	v_mul_f32_e32 v13, v13, v135
	v_mul_f32_e32 v14, v14, v135
	v_mul_f32_e32 v15, v15, v135
	v_mul_f32_e32 v0, v0, v135
	v_mul_f32_e32 v1, v1, v135
	v_mul_f32_e32 v2, v2, v135
	v_mul_f32_e32 v3, v3, v135
	v_fmac_f32_e32 v180, v12, v148
	v_fmac_f32_e32 v181, v13, v149
	v_fmac_f32_e32 v182, v14, v150
	v_fmac_f32_e32 v183, v15, v151
	v_fmac_f32_e32 v184, v0, v152
	v_fmac_f32_e32 v185, v1, v153
	v_fmac_f32_e32 v186, v2, v154
	v_fmac_f32_e32 v187, v3, v155
	global_store_dwordx4 v140, v[180:183], s[22:23]
	global_store_dwordx4 v140, v[184:187], s[22:23] offset:16
	v_lshlrev_b32_e32 v164, 16, v248
	v_and_b32_e32 v165, 0xffff0000, v248
	v_lshlrev_b32_e32 v166, 16, v249
	v_and_b32_e32 v167, 0xffff0000, v249
	v_lshlrev_b32_e32 v168, 16, v250
	v_and_b32_e32 v169, 0xffff0000, v250
	v_lshlrev_b32_e32 v170, 16, v251
	v_and_b32_e32 v171, 0xffff0000, v251
	v_mul_f32_e32 v4, v4, v135
	v_mul_f32_e32 v5, v5, v135
	v_mul_f32_e32 v6, v6, v135
	v_mul_f32_e32 v7, v7, v135
	v_mul_f32_e32 v8, v8, v135
	v_mul_f32_e32 v9, v9, v135
	v_mul_f32_e32 v10, v10, v135
	v_mul_f32_e32 v11, v11, v135
	v_fmac_f32_e32 v164, v4, v156
	v_fmac_f32_e32 v165, v5, v157
	v_fmac_f32_e32 v166, v6, v158
	v_fmac_f32_e32 v167, v7, v159
	v_fmac_f32_e32 v168, v8, v160
	v_fmac_f32_e32 v169, v9, v161
	v_fmac_f32_e32 v170, v10, v162
	v_fmac_f32_e32 v171, v11, v163
	global_store_dwordx4 v140, v[164:167], s[22:23] offset:512
	global_store_dwordx4 v140, v[168:171], s[22:23] offset:528
	s_addk_i32 s2, 0x400
	s_cmpk_ge_u32 s2, 0x420
	s_cselect_b64 vcc, -1, 0
	s_cbranch_vccnz .LBB0_1475
	v_and_b32_e32 v4, 63, v136
	v_ashrrev_i32_e32 v0, 5, v136
	v_readlane_b32 s4, v253, 3
	v_and_b32_e32 v5, -2, v0
	v_lshlrev_b32_e32 v0, 4, v4
	v_mov_b32_e32 v1, 0
	v_readlane_b32 s5, v253, 4
	s_mov_b64 s[0:1], 0x5000
	v_xor_b32_e32 v6, 32, v137
	v_lshl_add_u64 v[2:3], s[4:5], 0, v[0:1]
	v_lshl_add_u64 v[16:17], v[2:3], 0, s[0:1]
	v_and_b32_e32 v3, 64, v137
	v_add_u32_e32 v3, 64, v3
	v_cmp_lt_i32_e64 s[0:1], v6, v3
	v_readlane_b32 s6, v253, 5
	v_readlane_b32 s7, v253, 6
	v_cndmask_b32_e64 v6, v137, v6, s[0:1]
	v_lshlrev_b32_e32 v29, 2, v6
	v_xor_b32_e32 v6, 16, v137
	v_cmp_lt_i32_e64 s[0:1], v6, v3
	v_readlane_b32 s8, v253, 7
	v_readlane_b32 s9, v253, 8
	v_cndmask_b32_e64 v6, v137, v6, s[0:1]
	v_lshlrev_b32_e32 v50, 2, v6
	v_xor_b32_e32 v6, 8, v137
	v_cmp_lt_i32_e64 s[0:1], v6, v3
	v_readlane_b32 s10, v253, 9
	v_readlane_b32 s11, v253, 10
	v_cndmask_b32_e64 v6, v137, v6, s[0:1]
	v_lshlrev_b32_e32 v51, 2, v6
	v_xor_b32_e32 v6, 4, v137
	v_cmp_lt_i32_e64 s[0:1], v6, v3
	v_readlane_b32 s12, v253, 11
	v_readlane_b32 s13, v253, 12
	v_cndmask_b32_e64 v6, v137, v6, s[0:1]
	v_lshlrev_b32_e32 v52, 2, v6
	v_xor_b32_e32 v6, 2, v137
	v_cmp_lt_i32_e64 s[0:1], v6, v3
	v_readlane_b32 s14, v253, 13
	v_readlane_b32 s15, v253, 14
	v_cndmask_b32_e64 v6, v137, v6, s[0:1]
	v_lshlrev_b32_e32 v53, 2, v6
	v_xor_b32_e32 v6, 1, v137
	v_cmp_lt_i32_e64 s[0:1], v6, v3
	v_readlane_b32 s16, v253, 15
	v_readlane_b32 s17, v253, 16
	v_readlane_b32 s18, v253, 17
	v_readlane_b32 s19, v253, 18
	v_mul_u32_u24_e32 v2, 0x4200, v4
	v_cndmask_b32_e64 v3, v137, v6, s[0:1]
	v_lshlrev_b32_e32 v54, 2, v3
	v_lshlrev_b32_e32 v2, 2, v2
	v_mov_b32_e32 v3, v1
	v_readlane_b32 s4, v254, 52
	v_lshl_add_u64 v[18:19], s[44:45], 0, v[2:3]
	v_lshlrev_b32_e32 v2, 3, v4
	v_readlane_b32 s5, v254, 53
	v_cmp_gt_u32_e32 vcc, 16, v4
	v_lshl_add_u64 v[20:21], s[64:65], 0, v[2:3]
	v_lshl_add_u64 v[22:23], s[58:59], 0, v[2:3]
	v_lshl_add_u64 v[24:25], s[4:5], 0, v[0:1]
	v_lshl_add_u32 v26, s2, 4, v5
	s_lshl_b32 s3, s38, 4
	s_mov_b32 s4, 0x3a800000
	s_mov_b32 s5, 0x800000
	v_mov_b32_e32 v28, 0x358637bd
	v_readlane_b32 s6, v254, 54
	v_readlane_b32 s7, v254, 55
	v_readlane_b32 s8, v254, 56
	v_readlane_b32 s9, v254, 57
	v_readlane_b32 s10, v254, 58
	v_readlane_b32 s11, v254, 59
	v_readlane_b32 s12, v254, 60
	v_readlane_b32 s13, v254, 61
	v_readlane_b32 s14, v254, 62
	v_readlane_b32 s15, v254, 63
	v_readlane_b32 s16, v255, 0
	v_readlane_b32 s17, v255, 1
	v_readlane_b32 s18, v255, 2
	v_readlane_b32 s19, v255, 3
	s_branch .LBB0_1471
